# nt hint on the P9 (Hyena FFT) streaming input loads of the in-proj output, to keep OG2 resident for P10
# baseline (speedup 1.0000x reference)
.LBB0_1791:
	s_getreg_b32 s0, hwreg(HW_REG_HW_ID, 0, 6)
	s_lshl_b32 s0, s0, 2
	s_and_b32 s0, s0, 0xfc
	s_add_i32 s0, s0, 0
	s_add_i32 s0, s0, 0x256c0
	v_mov_b32_e32 v0, s0
	ds_read_b32 v0, v0
	s_ashr_i32 s45, s44, 31
	s_lshl_b64 s[0:1], s[44:45], 2
	s_add_u32 s46, s36, s0
	s_addc_u32 s47, s37, s1
	s_waitcnt lgkmcnt(0)
	v_readfirstlane_b32 s4, v0
	v_mbcnt_lo_u32_b32 v1, -1, 0
	v_mbcnt_hi_u32_b32 v1, -1, v1
	s_add_u32 s48, s38, s0
	s_addc_u32 s49, s39, s1
	v_lshl_add_u32 v209, s4, 6, v1
	s_lshl_b64 s[0:1], s[44:45], 13
	v_lshlrev_b32_e32 v0, 3, v209
	v_ashrrev_i32_e32 v1, 31, v0
	s_add_u32 s0, s12, s0
	s_addc_u32 s1, s13, s1
	v_lshlrev_b64 v[2:3], 1, v[0:1]
	s_waitcnt vmcnt(0)
	v_lshl_add_u64 v[22:23], s[0:1], 0, v[2:3]
	v_add_co_u32_e32 v8, vcc, s64, v22
	v_lshl_add_u64 v[16:17], v[22:23], 0, s[22:23]
	s_nop 0
	v_addc_co_u32_e32 v9, vcc, 0, v23, vcc
	s_add_i32 s50, s44, 0x2000
	global_load_dwordx4 v[4:7], v[22:23], off nt
	global_load_dwordx4 v[18:21], v[8:9], off nt
	s_nop 0
	global_load_ushort v9, v[16:17], off offset:-2 nt
	global_load_ushort v11, v[22:23], off offset:16 nt
	global_load_ushort v13, v[22:23], off offset:-2 nt
	s_ashr_i32 s51, s50, 31
	v_mov_b32_e32 v8, 0x3000
	s_lshl_b64 s[0:1], s[50:51], 13
	global_load_dword v8, v8, s[46:47]
	s_nop 0
	global_load_dword v10, v172, s[46:47]
	s_add_u32 s0, s12, s0
	s_addc_u32 s1, s13, s1
	v_mov_b32_e32 v12, 0x6000
	v_lshl_add_u64 v[34:35], s[0:1], 0, v[2:3]
	global_load_dword v14, v12, s[46:47]
	s_nop 0
	global_load_dword v12, v172, s[48:49]
	global_load_ushort v15, v[34:35], off offset:-2 nt
	global_load_ushort v62, v[16:17], off offset:16 nt
	v_lshl_add_u64 v[16:17], v[0:1], 2, s[16:17]
	v_add_co_u32_e32 v0, vcc, s65, v22
	v_cmp_lt_i32_e64 s[0:1], 0, v209
	s_nop 0
	v_addc_co_u32_e32 v1, vcc, 0, v23, vcc
	v_add_co_u32_e32 v40, vcc, s66, v22
	v_lshl_add_u64 v[36:37], v[22:23], 0, s[24:25]
	s_nop 0
	v_addc_co_u32_e32 v41, vcc, 0, v23, vcc
	v_add_co_u32_e32 v2, vcc, s67, v22
	v_lshl_add_u64 v[38:39], v[22:23], 0, s[28:29]
	s_nop 0
	v_addc_co_u32_e32 v3, vcc, 0, v23, vcc
	v_add_co_u32_e32 v46, vcc, s68, v22
	v_lshl_add_u64 v[42:43], v[22:23], 0, s[30:31]
	s_nop 0
	v_addc_co_u32_e32 v47, vcc, 0, v23, vcc
	v_add_co_u32_e32 v30, vcc, s69, v22
	v_lshl_add_u64 v[44:45], v[22:23], 0, s[40:41]
	s_nop 0
	v_addc_co_u32_e32 v31, vcc, 0, v23, vcc
	v_lshl_add_u64 v[48:49], v[22:23], 0, s[42:43]
	global_load_dwordx4 v[22:25], v[0:1], off nt
	global_load_dwordx4 v[26:29], v[2:3], off nt
	s_nop 0
	global_load_dwordx4 v[0:3], v[30:31], off nt
	s_nop 0
	global_load_dwordx4 v[30:33], v[34:35], off nt
	global_load_ushort v63, v[36:37], off offset:-2 nt
	v_cmp_gt_i32_e32 vcc, s63, v209
	s_mov_b32 s6, 0
	s_add_i32 s45, s44, 0xc00
	s_add_i32 s51, s44, 0x2c00
	s_mov_b64 s[52:53], 0
	s_mov_b64 s[54:55], -1
	s_waitcnt vmcnt(0)
	v_lshlrev_b32_e32 v9, 16, v9
	v_lshlrev_b32_e32 v50, 16, v5
	v_lshlrev_b32_e32 v13, 16, v13
	v_and_b32_e32 v52, 0xffff0000, v5
	v_and_b32_e32 v56, 0xffff0000, v4
	v_lshlrev_b32_e32 v51, 16, v19
	v_and_b32_e32 v53, 0xffff0000, v19
	v_and_b32_e32 v57, 0xffff0000, v18
	v_lshlrev_b32_e32 v5, 16, v18
	v_cndmask_b32_e64 v18, 0, v13, s[0:1]
	v_cndmask_b32_e64 v19, 0, v9, s[0:1]
	v_lshlrev_b32_e32 v4, 16, v4
	v_pk_mul_f32 v[58:59], v[8:9], v[56:57] op_sel_hi:[0,1]
	v_pk_mul_f32 v[60:61], v[8:9], v[50:51] op_sel_hi:[0,1]
	v_pk_mul_f32 v[18:19], v[10:11], v[18:19] op_sel_hi:[0,1]
	v_pk_fma_f32 v[58:59], v[10:11], v[4:5], v[58:59] op_sel_hi:[0,1,1]
	v_pk_fma_f32 v[60:61], v[10:11], v[56:57], v[60:61] op_sel_hi:[0,1,1]
	v_pk_fma_f32 v[4:5], v[8:9], v[4:5], v[18:19] op_sel_hi:[0,1,1]
	v_pk_fma_f32 v[18:19], v[14:15], v[50:51], v[58:59] op_sel_hi:[0,1,1]
	v_pk_fma_f32 v[58:59], v[14:15], v[52:53], v[60:61] op_sel_hi:[0,1,1]
	v_pk_fma_f32 v[4:5], v[14:15], v[56:57], v[4:5] op_sel_hi:[0,1,1]
	v_pk_add_f32 v[56:57], v[12:13], v[18:19] op_sel_hi:[0,1]
	v_pk_add_f32 v[58:59], v[12:13], v[58:59] op_sel_hi:[0,1]
	v_pk_add_f32 v[4:5], v[12:13], v[4:5] op_sel_hi:[0,1]
	v_pk_mul_f32 v[18:19], v[8:9], v[52:53] op_sel_hi:[0,1]
	global_load_ushort v9, v[36:37], off offset:16 nt
	global_load_ushort v13, v[34:35], off offset:16 nt
	v_lshlrev_b32_e32 v54, 16, v6
	v_lshlrev_b32_e32 v55, 16, v20
	v_pk_fma_f32 v[18:19], v[10:11], v[50:51], v[18:19] op_sel_hi:[0,1,1]
	v_pk_fma_f32 v[18:19], v[14:15], v[54:55], v[18:19] op_sel_hi:[0,1,1]
	v_lshlrev_b32_e32 v11, 16, v11
	v_and_b32_e32 v37, 0xffff0000, v21
	v_and_b32_e32 v36, 0xffff0000, v7
	v_and_b32_e32 v6, 0xffff0000, v6
	v_lshlrev_b32_e32 v51, 16, v62
	v_cndmask_b32_e32 v50, 0, v11, vcc
	v_cndmask_b32_e32 v51, 0, v51, vcc
	s_waitcnt vmcnt(0)
	v_pk_add_f32 v[34:35], v[12:13], v[18:19] op_sel_hi:[0,1]
	v_lshlrev_b32_e32 v19, 16, v21
	v_lshlrev_b32_e32 v18, 16, v7
	v_and_b32_e32 v7, 0xffff0000, v20
	v_pk_mul_f32 v[20:21], v[8:9], v[54:55] op_sel_hi:[0,1]
	v_pk_fma_f32 v[20:21], v[10:11], v[52:53], v[20:21] op_sel_hi:[0,1,1]
	v_pk_fma_f32 v[20:21], v[14:15], v[6:7], v[20:21] op_sel_hi:[0,1,1]
	v_pk_add_f32 v[52:53], v[12:13], v[20:21] op_sel_hi:[0,1]
	v_pk_mul_f32 v[20:21], v[8:9], v[6:7] op_sel_hi:[0,1]
	v_pk_fma_f32 v[20:21], v[10:11], v[54:55], v[20:21] op_sel_hi:[0,1,1]
	v_pk_fma_f32 v[20:21], v[14:15], v[18:19], v[20:21] op_sel_hi:[0,1,1]
	v_pk_add_f32 v[54:55], v[12:13], v[20:21] op_sel_hi:[0,1]
	v_pk_mul_f32 v[20:21], v[8:9], v[18:19] op_sel_hi:[0,1]
	v_pk_fma_f32 v[6:7], v[10:11], v[6:7], v[20:21] op_sel_hi:[0,1,1]
	v_pk_fma_f32 v[6:7], v[14:15], v[36:37], v[6:7] op_sel_hi:[0,1,1]
	v_pk_add_f32 v[60:61], v[12:13], v[6:7] op_sel_hi:[0,1]
	v_pk_mul_f32 v[6:7], v[8:9], v[36:37] op_sel_hi:[0,1]
	v_pk_fma_f32 v[6:7], v[10:11], v[18:19], v[6:7] op_sel_hi:[0,1,1]
	v_pk_fma_f32 v[6:7], v[14:15], v[50:51], v[6:7] op_sel_hi:[0,1,1]
	v_pk_add_f32 v[50:51], v[12:13], v[6:7] op_sel_hi:[0,1]
	v_cvt_pk_f16_f32 v18, v4, v5
	v_cvt_pk_f16_f32 v19, v56, v57
	v_cvt_pk_f16_f32 v20, v58, v59
	v_cvt_pk_f16_f32 v21, v34, v35
	global_load_dwordx4 v[34:37], v[40:41], off nt
	global_load_ushort v11, v[42:43], off offset:-2 nt
	global_load_ushort v56, v[42:43], off offset:16 nt
	global_load_ushort v57, v[38:39], off offset:-2 nt
	global_load_ushort v58, v[38:39], off offset:16 nt
	global_load_dwordx4 v[4:7], v[46:47], off nt
	global_load_ushort v59, v[48:49], off offset:-2 nt
	s_nop 0
	global_load_ushort v48, v[48:49], off offset:16 nt
	s_nop 0
	global_load_ushort v49, v[44:45], off offset:-2 nt
	global_load_ushort v62, v[44:45], off offset:16 nt
	v_lshlrev_b32_e32 v15, 16, v15
	global_store_dwordx4 v[16:17], v[18:21], off
	v_and_b32_e32 v41, 0xffff0000, v22
	v_and_b32_e32 v40, 0xffff0000, v30
	v_cvt_pk_f16_f32 v18, v52, v53
	v_cvt_pk_f16_f32 v19, v54, v55
	v_cvt_pk_f16_f32 v20, v60, v61
	v_cvt_pk_f16_f32 v21, v50, v51
	global_store_dwordx4 v[16:17], v[18:21], off offset:16
	v_lshlrev_b32_e32 v30, 16, v30
	v_pk_mul_f32 v[42:43], v[8:9], v[40:41] op_sel_hi:[0,1]
	v_lshlrev_b32_e32 v19, 16, v23
	v_and_b32_e32 v21, 0xffff0000, v23
	v_lshlrev_b32_e32 v23, 16, v63
	v_lshlrev_b32_e32 v18, 16, v31
	v_and_b32_e32 v20, 0xffff0000, v31
	v_lshlrev_b32_e32 v31, 16, v22
	v_cndmask_b32_e64 v22, 0, v15, s[0:1]
	v_cndmask_b32_e64 v23, 0, v23, s[0:1]
	v_lshlrev_b32_e32 v38, 16, v32
	v_lshlrev_b32_e32 v39, 16, v24
	v_and_b32_e32 v45, 0xffff0000, v25
	v_and_b32_e32 v44, 0xffff0000, v33
	s_waitcnt vmcnt(10)
	v_pk_mul_f32 v[22:23], v[10:11], v[22:23] op_sel_hi:[0,1]
	v_pk_fma_f32 v[22:23], v[8:9], v[30:31], v[22:23] op_sel_hi:[0,1,1]
	v_pk_fma_f32 v[30:31], v[10:11], v[30:31], v[42:43] op_sel_hi:[0,1,1]
	v_pk_mul_f32 v[42:43], v[8:9], v[18:19] op_sel_hi:[0,1]
	v_pk_fma_f32 v[22:23], v[14:15], v[40:41], v[22:23] op_sel_hi:[0,1,1]
	v_pk_fma_f32 v[40:41], v[10:11], v[40:41], v[42:43] op_sel_hi:[0,1,1]
	v_pk_mul_f32 v[42:43], v[8:9], v[20:21] op_sel_hi:[0,1]
	v_pk_fma_f32 v[30:31], v[14:15], v[18:19], v[30:31] op_sel_hi:[0,1,1]
	v_pk_fma_f32 v[18:19], v[10:11], v[18:19], v[42:43] op_sel_hi:[0,1,1]
	v_pk_fma_f32 v[18:19], v[14:15], v[38:39], v[18:19] op_sel_hi:[0,1,1]
	v_lshlrev_b32_e32 v9, 16, v9
	v_pk_add_f32 v[42:43], v[12:13], v[18:19] op_sel_hi:[0,1]
	v_lshlrev_b32_e32 v18, 16, v33
	v_lshlrev_b32_e32 v19, 16, v25
	v_and_b32_e32 v25, 0xffff0000, v24
	v_and_b32_e32 v24, 0xffff0000, v32
	v_pk_mul_f32 v[32:33], v[8:9], v[38:39] op_sel_hi:[0,1]
	v_pk_fma_f32 v[40:41], v[14:15], v[20:21], v[40:41] op_sel_hi:[0,1,1]
	v_pk_fma_f32 v[20:21], v[10:11], v[20:21], v[32:33] op_sel_hi:[0,1,1]
	v_pk_add_f32 v[22:23], v[12:13], v[22:23] op_sel_hi:[0,1]
	v_pk_add_f32 v[30:31], v[12:13], v[30:31] op_sel_hi:[0,1]
	v_pk_add_f32 v[40:41], v[12:13], v[40:41] op_sel_hi:[0,1]
	v_lshlrev_b32_e32 v13, 16, v13
	v_pk_fma_f32 v[20:21], v[14:15], v[24:25], v[20:21] op_sel_hi:[0,1,1]
	v_pk_add_f32 v[32:33], v[12:13], v[20:21] op_sel_hi:[0,1]
	v_pk_mul_f32 v[20:21], v[8:9], v[24:25] op_sel_hi:[0,1]
	v_pk_fma_f32 v[20:21], v[10:11], v[38:39], v[20:21] op_sel_hi:[0,1,1]
	v_pk_fma_f32 v[20:21], v[14:15], v[18:19], v[20:21] op_sel_hi:[0,1,1]
	v_pk_add_f32 v[38:39], v[12:13], v[20:21] op_sel_hi:[0,1]
	v_pk_mul_f32 v[20:21], v[8:9], v[18:19] op_sel_hi:[0,1]
	v_pk_fma_f32 v[20:21], v[10:11], v[24:25], v[20:21] op_sel_hi:[0,1,1]
	v_pk_fma_f32 v[20:21], v[14:15], v[44:45], v[20:21] op_sel_hi:[0,1,1]
	v_pk_add_f32 v[24:25], v[12:13], v[20:21] op_sel_hi:[0,1]
	v_pk_mul_f32 v[20:21], v[8:9], v[44:45] op_sel_hi:[0,1]
	v_cndmask_b32_e32 v46, 0, v13, vcc
	v_cndmask_b32_e32 v47, 0, v9, vcc
	v_pk_fma_f32 v[18:19], v[10:11], v[18:19], v[20:21] op_sel_hi:[0,1,1]
	v_pk_fma_f32 v[18:19], v[14:15], v[46:47], v[18:19] op_sel_hi:[0,1,1]
	v_pk_add_f32 v[44:45], v[12:13], v[18:19] op_sel_hi:[0,1]
	v_cvt_pk_f16_f32 v18, v22, v23
	v_add_co_u32_e64 v22, s[4:5], s72, v16
	v_cvt_pk_f16_f32 v19, v30, v31
	v_cvt_pk_f16_f32 v20, v40, v41
	v_cvt_pk_f16_f32 v21, v42, v43
	v_addc_co_u32_e64 v23, s[4:5], 0, v17, s[4:5]
	s_waitcnt vmcnt(8)
	v_lshlrev_b32_e32 v9, 16, v57
	v_lshlrev_b32_e32 v11, 16, v11
	global_store_dwordx4 v[22:23], v[18:21], off
	v_cndmask_b32_e64 v31, 0, v11, s[0:1]
	v_cndmask_b32_e64 v30, 0, v9, s[0:1]
	v_cvt_pk_f16_f32 v18, v32, v33
	v_cvt_pk_f16_f32 v19, v38, v39
	v_cvt_pk_f16_f32 v20, v24, v25
	v_cvt_pk_f16_f32 v21, v44, v45
	v_and_b32_e32 v25, 0xffff0000, v26
	v_and_b32_e32 v24, 0xffff0000, v34
	global_store_dwordx4 v[22:23], v[18:21], off offset:16
	v_pk_mul_f32 v[30:31], v[10:11], v[30:31] op_sel_hi:[0,1]
	v_pk_mul_f32 v[32:33], v[8:9], v[24:25] op_sel_hi:[0,1]
	v_lshlrev_b32_e32 v19, 16, v27
	v_lshlrev_b32_e32 v18, 16, v35
	v_and_b32_e32 v21, 0xffff0000, v27
	v_lshlrev_b32_e32 v27, 16, v26
	v_lshlrev_b32_e32 v26, 16, v34
	v_and_b32_e32 v20, 0xffff0000, v35
	v_pk_fma_f32 v[30:31], v[8:9], v[26:27], v[30:31] op_sel_hi:[0,1,1]
	v_pk_fma_f32 v[26:27], v[10:11], v[26:27], v[32:33] op_sel_hi:[0,1,1]
	v_pk_mul_f32 v[32:33], v[8:9], v[18:19] op_sel_hi:[0,1]
	v_pk_fma_f32 v[30:31], v[14:15], v[24:25], v[30:31] op_sel_hi:[0,1,1]
	v_pk_fma_f32 v[24:25], v[10:11], v[24:25], v[32:33] op_sel_hi:[0,1,1]
	v_pk_mul_f32 v[32:33], v[8:9], v[20:21] op_sel_hi:[0,1]
	v_lshlrev_b32_e32 v23, 16, v28
	v_lshlrev_b32_e32 v22, 16, v36
	v_pk_fma_f32 v[26:27], v[14:15], v[18:19], v[26:27] op_sel_hi:[0,1,1]
	v_pk_fma_f32 v[18:19], v[10:11], v[18:19], v[32:33] op_sel_hi:[0,1,1]
	v_pk_fma_f32 v[18:19], v[14:15], v[22:23], v[18:19] op_sel_hi:[0,1,1]
	s_waitcnt vmcnt(9)
	v_lshlrev_b32_e32 v9, 16, v58
	v_pk_add_f32 v[32:33], v[12:13], v[18:19] op_sel_hi:[0,1]
	v_lshlrev_b32_e32 v11, 16, v56
	v_lshlrev_b32_e32 v19, 16, v29
	v_lshlrev_b32_e32 v18, 16, v37
	v_and_b32_e32 v35, 0xffff0000, v29
	v_and_b32_e32 v34, 0xffff0000, v37
	v_and_b32_e32 v29, 0xffff0000, v28
	v_and_b32_e32 v28, 0xffff0000, v36
	v_pk_mul_f32 v[36:37], v[8:9], v[22:23] op_sel_hi:[0,1]
	v_pk_fma_f32 v[24:25], v[14:15], v[20:21], v[24:25] op_sel_hi:[0,1,1]
	v_pk_fma_f32 v[20:21], v[10:11], v[20:21], v[36:37] op_sel_hi:[0,1,1]
	v_pk_fma_f32 v[20:21], v[14:15], v[28:29], v[20:21] op_sel_hi:[0,1,1]
	v_pk_add_f32 v[36:37], v[12:13], v[20:21] op_sel_hi:[0,1]
	v_pk_mul_f32 v[20:21], v[8:9], v[28:29] op_sel_hi:[0,1]
	v_pk_fma_f32 v[20:21], v[10:11], v[22:23], v[20:21] op_sel_hi:[0,1,1]
	v_pk_fma_f32 v[20:21], v[14:15], v[18:19], v[20:21] op_sel_hi:[0,1,1]
	v_pk_add_f32 v[22:23], v[12:13], v[20:21] op_sel_hi:[0,1]
	v_pk_mul_f32 v[20:21], v[8:9], v[18:19] op_sel_hi:[0,1]
	v_pk_fma_f32 v[20:21], v[10:11], v[28:29], v[20:21] op_sel_hi:[0,1,1]
	v_pk_fma_f32 v[20:21], v[14:15], v[34:35], v[20:21] op_sel_hi:[0,1,1]
	v_pk_add_f32 v[28:29], v[12:13], v[20:21] op_sel_hi:[0,1]
	v_pk_mul_f32 v[20:21], v[8:9], v[34:35] op_sel_hi:[0,1]
	v_pk_add_f32 v[24:25], v[12:13], v[24:25] op_sel_hi:[0,1]
	v_cndmask_b32_e32 v39, 0, v11, vcc
	v_cndmask_b32_e32 v38, 0, v9, vcc
	v_pk_fma_f32 v[18:19], v[10:11], v[18:19], v[20:21] op_sel_hi:[0,1,1]
	v_pk_add_f32 v[30:31], v[12:13], v[30:31] op_sel_hi:[0,1]
	v_pk_add_f32 v[26:27], v[12:13], v[26:27] op_sel_hi:[0,1]
	v_pk_fma_f32 v[18:19], v[14:15], v[38:39], v[18:19] op_sel_hi:[0,1,1]
	v_cvt_pk_f16_f32 v20, v24, v25
	v_add_co_u32_e64 v24, s[4:5], s73, v16
	v_pk_add_f32 v[34:35], v[12:13], v[18:19] op_sel_hi:[0,1]
	v_cvt_pk_f16_f32 v18, v30, v31
	v_cvt_pk_f16_f32 v19, v26, v27
	v_cvt_pk_f16_f32 v21, v32, v33
	v_addc_co_u32_e64 v25, s[4:5], 0, v17, s[4:5]
	global_store_dwordx4 v[24:25], v[18:21], off
	s_nop 1
	v_cvt_pk_f16_f32 v18, v36, v37
	v_cvt_pk_f16_f32 v19, v22, v23
	v_cvt_pk_f16_f32 v20, v28, v29
	v_cvt_pk_f16_f32 v21, v34, v35
	global_store_dwordx4 v[24:25], v[18:21], off offset:16
	v_and_b32_e32 v25, 0xffff0000, v0
	s_waitcnt vmcnt(10)
	v_and_b32_e32 v24, 0xffff0000, v4
	v_lshlrev_b32_e32 v19, 16, v1
	v_lshlrev_b32_e32 v18, 16, v5
	v_and_b32_e32 v21, 0xffff0000, v1
	v_and_b32_e32 v20, 0xffff0000, v5
	v_lshlrev_b32_e32 v1, 16, v0
	v_lshlrev_b32_e32 v0, 16, v4
	s_waitcnt vmcnt(7)
	v_lshlrev_b32_e32 v4, 16, v49
	v_lshlrev_b32_e32 v5, 16, v59
	v_cndmask_b32_e64 v5, 0, v5, s[0:1]
	v_cndmask_b32_e64 v4, 0, v4, s[0:1]
	v_pk_mul_f32 v[4:5], v[10:11], v[4:5] op_sel_hi:[0,1]
	v_pk_mul_f32 v[26:27], v[8:9], v[24:25] op_sel_hi:[0,1]
	v_pk_fma_f32 v[4:5], v[8:9], v[0:1], v[4:5] op_sel_hi:[0,1,1]
	v_pk_fma_f32 v[0:1], v[10:11], v[0:1], v[26:27] op_sel_hi:[0,1,1]
	v_pk_fma_f32 v[0:1], v[14:15], v[18:19], v[0:1] op_sel_hi:[0,1,1]
	v_pk_add_f32 v[26:27], v[12:13], v[0:1] op_sel_hi:[0,1]
	v_pk_mul_f32 v[0:1], v[8:9], v[18:19] op_sel_hi:[0,1]
	v_pk_fma_f32 v[0:1], v[10:11], v[24:25], v[0:1] op_sel_hi:[0,1,1]
	v_pk_fma_f32 v[0:1], v[14:15], v[20:21], v[0:1] op_sel_hi:[0,1,1]
	v_pk_fma_f32 v[4:5], v[14:15], v[24:25], v[4:5] op_sel_hi:[0,1,1]
	v_pk_add_f32 v[24:25], v[12:13], v[0:1] op_sel_hi:[0,1]
	v_pk_mul_f32 v[0:1], v[8:9], v[20:21] op_sel_hi:[0,1]
	v_lshlrev_b32_e32 v23, 16, v2
	v_lshlrev_b32_e32 v22, 16, v6
	v_pk_fma_f32 v[0:1], v[10:11], v[18:19], v[0:1] op_sel_hi:[0,1,1]
	v_pk_fma_f32 v[0:1], v[14:15], v[22:23], v[0:1] op_sel_hi:[0,1,1]
	s_waitcnt vmcnt(6)
	v_lshlrev_b32_e32 v9, 16, v62
	v_pk_add_f32 v[18:19], v[12:13], v[0:1] op_sel_hi:[0,1]
	v_lshlrev_b32_e32 v11, 16, v48
	v_lshlrev_b32_e32 v1, 16, v3
	v_lshlrev_b32_e32 v0, 16, v7
	v_and_b32_e32 v29, 0xffff0000, v3
	v_and_b32_e32 v28, 0xffff0000, v7
	v_and_b32_e32 v3, 0xffff0000, v2
	v_and_b32_e32 v2, 0xffff0000, v6
	v_pk_mul_f32 v[6:7], v[8:9], v[22:23] op_sel_hi:[0,1]
	v_pk_fma_f32 v[6:7], v[10:11], v[20:21], v[6:7] op_sel_hi:[0,1,1]
	v_pk_mul_f32 v[20:21], v[8:9], v[2:3] op_sel_hi:[0,1]
	v_pk_fma_f32 v[20:21], v[10:11], v[22:23], v[20:21] op_sel_hi:[0,1,1]
	v_pk_mul_f32 v[22:23], v[8:9], v[0:1] op_sel_hi:[0,1]
	v_pk_fma_f32 v[6:7], v[14:15], v[2:3], v[6:7] op_sel_hi:[0,1,1]
	v_pk_fma_f32 v[2:3], v[10:11], v[2:3], v[22:23] op_sel_hi:[0,1,1]
	v_pk_fma_f32 v[2:3], v[14:15], v[28:29], v[2:3] op_sel_hi:[0,1,1]
	v_pk_add_f32 v[22:23], v[12:13], v[2:3] op_sel_hi:[0,1]
	v_pk_mul_f32 v[2:3], v[8:9], v[28:29] op_sel_hi:[0,1]
	v_cndmask_b32_e32 v31, 0, v11, vcc
	v_cndmask_b32_e32 v30, 0, v9, vcc
	v_pk_fma_f32 v[20:21], v[14:15], v[0:1], v[20:21] op_sel_hi:[0,1,1]
	v_pk_fma_f32 v[0:1], v[10:11], v[0:1], v[2:3] op_sel_hi:[0,1,1]
	v_pk_add_f32 v[4:5], v[12:13], v[4:5] op_sel_hi:[0,1]
	v_pk_fma_f32 v[0:1], v[14:15], v[30:31], v[0:1] op_sel_hi:[0,1,1]
	v_pk_add_f32 v[8:9], v[12:13], v[0:1] op_sel_hi:[0,1]
	v_cvt_pk_f16_f32 v0, v4, v5
	v_add_co_u32_e32 v4, vcc, s80, v16
	v_pk_add_f32 v[6:7], v[12:13], v[6:7] op_sel_hi:[0,1]
	v_pk_add_f32 v[20:21], v[12:13], v[20:21] op_sel_hi:[0,1]
	v_cvt_pk_f16_f32 v1, v26, v27
	v_cvt_pk_f16_f32 v2, v24, v25
	v_cvt_pk_f16_f32 v3, v18, v19
	v_addc_co_u32_e32 v5, vcc, 0, v17, vcc
	global_store_dwordx4 v[4:5], v[0:3], off
	s_nop 1
	v_cvt_pk_f16_f32 v0, v6, v7
	v_cvt_pk_f16_f32 v1, v20, v21
	v_cvt_pk_f16_f32 v2, v22, v23
	v_cvt_pk_f16_f32 v3, v8, v9
	global_store_dwordx4 v[4:5], v[0:3], off offset:16
	s_barrier
	s_branch .LBB0_1793

.LBB0_1793:
	s_add_i32 s0, s6, s44
	s_ashr_i32 s1, s0, 31
	v_and_b32_e32 v0, 0x1fdf, v209
	s_xor_b64 s[56:57], s[54:55], -1
	v_bfe_u32 v36, v209, 5, 1
	s_lshl_b64 s[4:5], s[0:1], 14
	v_sub_u32_e32 v1, 0, v0
	v_mov_b32_e32 v3, 0xfffffe00
	v_mov_b32_e32 v5, 0xfffffc00
	v_mov_b32_e32 v7, 0xfffffa00
	v_sub_u32_e32 v0, 0x1fe0, v0
	s_add_u32 s4, s26, s4
	v_xor_b32_e32 v1, 0x1000, v1
	v_mad_u32_u24 v3, v36, s81, v3
	v_mad_u32_u24 v5, v36, s81, v5
	v_mad_u32_u24 v7, v36, s81, v7
	v_mad_u32_u24 v9, v36, s81, v205
	v_mad_u32_u24 v11, v36, s81, v206
	v_mad_u32_u24 v13, v36, s81, v207
	v_mad_u32_u24 v15, v36, s81, v208
	v_xor_b32_e32 v0, 0x1000, v0
	s_addc_u32 s5, s27, s5
	v_mad_u32_u24 v2, v36, s81, v1
	v_add_u32_e32 v4, v3, v1
	v_add_u32_e32 v6, v5, v1
	v_add_u32_e32 v8, v7, v1
	v_add_u32_e32 v10, v9, v1
	v_add_u32_e32 v12, v11, v1
	v_add_u32_e32 v14, v13, v1
	v_add_u32_e32 v1, v15, v1
	s_waitcnt vmcnt(1)
	v_mad_u32_u24 v16, v36, s81, v0
	v_add_u32_e32 v3, v3, v0
	v_add_u32_e32 v5, v5, v0
	v_add_u32_e32 v7, v7, v0
	v_add_u32_e32 v9, v9, v0
	v_add_u32_e32 v11, v11, v0
	v_add_u32_e32 v13, v13, v0
	s_lshl_b64 s[0:1], s[0:1], 2
	v_add_u32_e32 v0, v15, v0
	v_and_b32_e32 v2, 0x1fff, v2
	v_and_b32_e32 v4, 0x1fff, v4
	v_and_b32_e32 v6, 0x1fff, v6
	v_and_b32_e32 v8, 0x1fff, v8
	v_and_b32_e32 v10, 0x1fff, v10
	v_and_b32_e32 v12, 0x1fff, v12
	v_and_b32_e32 v14, 0x1fff, v14
	v_and_b32_e32 v1, 0x1fff, v1
	v_and_b32_e32 v16, 0x1fff, v16
	v_and_b32_e32 v3, 0x1fff, v3
	v_and_b32_e32 v5, 0x1fff, v5
	v_and_b32_e32 v7, 0x1fff, v7
	v_and_b32_e32 v9, 0x1fff, v9
	v_and_b32_e32 v11, 0x1fff, v11
	v_and_b32_e32 v13, 0x1fff, v13
	s_add_u32 s6, s3, s0
	v_and_b32_e32 v0, 0x1fff, v0
	v_lshlrev_b32_e32 v2, 1, v2
	v_lshlrev_b32_e32 v4, 1, v4
	v_lshlrev_b32_e32 v6, 1, v6
	v_lshlrev_b32_e32 v8, 1, v8
	v_lshlrev_b32_e32 v10, 1, v10
	v_lshlrev_b32_e32 v12, 1, v12
	v_lshlrev_b32_e32 v14, 1, v14
	v_lshlrev_b32_e32 v1, 1, v1
	v_lshlrev_b32_e32 v16, 1, v16
	v_lshlrev_b32_e32 v3, 1, v3
	v_lshlrev_b32_e32 v5, 1, v5
	v_lshlrev_b32_e32 v7, 1, v7
	v_lshlrev_b32_e32 v9, 1, v9
	v_lshlrev_b32_e32 v11, 1, v11
	v_lshlrev_b32_e32 v13, 1, v13
	v_lshlrev_b32_e32 v0, 1, v0
	s_addc_u32 s7, s62, s1
	global_load_ushort v2, v2, s[4:5]
	s_nop 0
	global_load_ushort v4, v4, s[4:5]
	s_nop 0
	global_load_ushort v6, v6, s[4:5]
	s_nop 0
	global_load_ushort v8, v8, s[4:5]
	s_nop 0
	global_load_ushort v10, v10, s[4:5]
	s_nop 0
	global_load_ushort v12, v12, s[4:5]
	s_nop 0
	global_load_ushort v14, v14, s[4:5]
	s_nop 0
	global_load_ushort v1, v1, s[4:5]
	s_nop 0
	global_load_ushort v16, v16, s[4:5]
	s_nop 0
	global_load_ushort v3, v3, s[4:5]
	s_nop 0
	global_load_ushort v5, v5, s[4:5]
	s_nop 0
	global_load_ushort v7, v7, s[4:5]
	s_nop 0
	global_load_ushort v9, v9, s[4:5]
	s_nop 0
	global_load_ushort v11, v11, s[4:5]
	s_nop 0
	global_load_ushort v13, v13, s[4:5]
	v_lshlrev_b32_e32 v32, 3, v209
	global_load_ushort v15, v0, s[4:5]
	global_load_dword v17, v172, s[6:7]
	v_ashrrev_i32_e32 v33, 31, v32
	v_lshlrev_b64 v[34:35], 2, v[32:33]
	v_lshl_add_u64 v[148:149], s[16:17], 0, v[34:35]
	v_add_co_u32_e32 v0, vcc, s72, v148
	v_mov_b32_e32 v43, v209
	s_add_u32 s0, s70, s0
	s_addc_u32 s1, s71, s1
	s_and_b64 s[4:5], s[54:55], exec
	s_cselect_b32 s91, s88, 0x800
	s_add_i32 s90, s91, s44
	s_mov_b64 s[58:59], -1
	v_lshl_add_u64 v[164:165], s[18:19], 0, v[34:35]
	v_lshl_add_u64 v[166:167], s[20:21], 0, v[34:35]
	s_mov_b32 s60, 0
	s_waitcnt vmcnt(9)
	v_lshlrev_b32_e32 v19, 16, v1
	v_addc_co_u32_e32 v1, vcc, 0, v149, vcc
	s_waitcnt vmcnt(7)
	v_lshlrev_b32_e32 v21, 16, v3
	s_waitcnt vmcnt(6)
	v_lshlrev_b32_e32 v22, 16, v5
	global_load_dwordx4 v[104:107], v[0:1], off nt
	global_load_dwordx4 v[108:111], v[148:149], off nt
	global_load_dwordx4 v[100:103], v[148:149], off offset:16 nt
	global_load_dwordx4 v[96:99], v[0:1], off offset:16 nt
	s_waitcnt vmcnt(9)
	v_lshlrev_b32_e32 v23, 16, v7
	v_lshlrev_b32_e32 v10, 16, v10
	v_lshlrev_b32_e32 v2, 16, v2
	s_waitcnt vmcnt(4)
	v_div_scale_f32 v3, s[4:5], v17, v17, s82
	v_rcp_f32_e32 v5, v3
	v_lshlrev_b32_e32 v4, 16, v4
	v_lshlrev_b32_e32 v6, 16, v6
	v_lshlrev_b32_e32 v8, 16, v8
	v_fma_f32 v0, -v3, v5, 1.0
	v_fmac_f32_e32 v5, v0, v5
	v_div_scale_f32 v0, vcc, s82, v17, s82
	v_mul_f32_e32 v1, v0, v5
	v_fma_f32 v7, -v3, v1, v0
	v_fmac_f32_e32 v1, v7, v5
	v_fma_f32 v0, -v3, v1, v0
	v_div_fmas_f32 v0, v0, v5, v1
	v_div_fixup_f32 v42, v0, v17, s82
	v_mul_f32_e32 v1, v42, v10
	v_lshlrev_b32_e32 v20, 16, v16
	v_mul_f32_e32 v0, v42, v2
	v_cvt_pk_f16_f32 v16, v1, 0
	v_mul_f32_e32 v1, v42, v4
	v_mul_f32_e32 v2, v42, v6
	v_mul_f32_e32 v3, v42, v8
	v_lshlrev_b32_e32 v12, 16, v12
	v_cvt_pk_f16_f32 v0, v0, 0
	v_cvt_pk_f16_f32 v1, v1, 0
	v_cvt_pk_f16_f32 v2, v2, 0
	v_cvt_pk_f16_f32 v3, v3, 0
	v_lshlrev_b32_e32 v18, 16, v14
	v_lshlrev_b32_e32 v24, 16, v9
	v_lshlrev_b32_e32 v37, 16, v11
	v_lshlrev_b32_e32 v40, 16, v13
	v_lshlrev_b32_e32 v41, 16, v15
	v_mul_f32_e32 v17, v42, v12
	v_mfma_f32_32x32x16_f16 v[0:15], v[68:71], v[0:3], 0
	v_mul_f32_e32 v18, v42, v18
	v_mul_f32_e32 v19, v42, v19
	v_cvt_pk_f16_f32 v17, v17, 0
	v_cvt_pk_f16_f32 v18, v18, 0
	v_cvt_pk_f16_f32 v19, v19, 0
	v_mul_f32_e32 v20, v42, v20
	v_cvt_pk_f16_f32 v20, v20, 0
	v_mfma_f32_32x32x16_f16 v[0:15], v[84:87], v[16:19], v[0:15]
	v_mul_f32_e32 v16, v42, v21
	v_cvt_pk_f16_f32 v21, v16, 0
	v_mul_f32_e32 v16, v42, v22
	v_cvt_pk_f16_f32 v22, v16, 0
	v_mul_f32_e32 v16, v42, v23
	v_cvt_pk_f16_f32 v23, v16, 0
	v_mul_f32_e32 v38, v42, v24
	v_mul_f32_e32 v37, v42, v37
	v_mfma_f32_32x32x16_f16 v[16:31], v[72:75], v[20:23], 0
	v_cvt_pk_f16_f32 v39, v37, 0
	v_mul_f32_e32 v37, v42, v40
	v_cvt_pk_f16_f32 v40, v37, 0
	v_mul_f32_e32 v37, v42, v41
	v_cvt_pk_f16_f32 v38, v38, 0
	v_cvt_pk_f16_f32 v41, v37, 0
	v_and_b32_e32 v37, 0xffffffdf, v209
	v_cvt_pk_f16_f32 v0, v0, v1
	v_mfma_f32_32x32x16_f16 v[16:31], v[88:91], v[38:41], v[16:31]
	v_lshrrev_b32_e32 v38, 2, v209
	v_and_b32_e32 v38, 8, v38
	v_add_u32_e32 v38, 0, v38
	v_mad_u64_u32 v[40:41], s[4:5], v37, s83, v[38:39]
	v_cvt_pk_f16_f32 v1, v2, v3
	ds_write2_b32 v40, v0, v1 offset1:1
	v_cvt_pk_f16_f32 v0, v4, v5
	v_cvt_pk_f16_f32 v1, v6, v7
	ds_write2_b32 v40, v0, v1 offset0:4 offset1:5
	v_cvt_pk_f16_f32 v0, v8, v9
	v_cvt_pk_f16_f32 v1, v10, v11
	ds_write2_b32 v40, v0, v1 offset0:8 offset1:9
	v_cvt_pk_f16_f32 v0, v12, v13
	v_cvt_pk_f16_f32 v1, v14, v15
	v_or_b32_e32 v42, 32, v209
	ds_write2_b32 v40, v0, v1 offset0:12 offset1:13
	v_mad_u64_u32 v[0:1], s[4:5], v42, s83, v[38:39]
	v_cvt_pk_f16_f32 v1, v16, v17
	v_cvt_pk_f16_f32 v2, v18, v19
	ds_write2_b32 v0, v1, v2 offset1:1
	v_cvt_pk_f16_f32 v1, v20, v21
	v_cvt_pk_f16_f32 v2, v22, v23
	ds_write2_b32 v0, v1, v2 offset0:4 offset1:5
	v_cvt_pk_f16_f32 v1, v24, v25
	v_cvt_pk_f16_f32 v2, v26, v27
	ds_write2_b32 v0, v1, v2 offset0:8 offset1:9
	v_cvt_pk_f16_f32 v1, v28, v29
	v_cvt_pk_f16_f32 v2, v30, v31
	ds_write2_b32 v0, v1, v2 offset0:12 offset1:13
	s_waitcnt lgkmcnt(0)
	s_barrier
	s_lshl_b32 s4, s91, 2
	v_and_b32_e32 v0, 0xffffffdf, v43
	v_bfe_u32 v44, v43, 5, 1
	v_ashrrev_i32_e32 v46, 4, v0
	v_mad_u32_u24 v45, v44, s84, 0
	v_add_u32_e32 v0, v46, v0
	v_lshl_add_u32 v5, v0, 2, v45
	ds_read_b32 v0, v5
	ds_read_b32 v1, v5 offset:2176
	ds_read_b32 v2, v5 offset:4352
	ds_read_b32 v3, v5 offset:6528
	ds_read_b32 v6, v5 offset:21760
	ds_read_b32 v7, v5 offset:23936
	ds_read_b32 v4, v5 offset:17408
	s_waitcnt lgkmcnt(3)
	v_mfma_f32_32x32x16_f16 v[16:31], v[64:67], v[0:3], 0
	v_or_b32_e32 v0, 32, v43
	ds_read_b32 v5, v5 offset:19584
	v_ashrrev_i32_e32 v47, 4, v0
	v_add_u32_e32 v0, v47, v0
	v_lshl_add_u32 v39, v0, 2, v45
	ds_read_b32 v0, v39
	ds_read_b32 v1, v39 offset:2176
	ds_read_b32 v2, v39 offset:4352
	ds_read_b32 v3, v39 offset:6528
	ds_read_b32 v40, v39 offset:21760
	ds_read_b32 v41, v39 offset:23936
	ds_read_b32 v38, v39 offset:17408
	ds_read_b32 v39, v39 offset:19584
	s_waitcnt lgkmcnt(8)
	v_mfma_f32_32x32x16_f16 v[16:31], v[80:83], v[4:7], v[16:31]
	s_nop 15
	s_nop 3
	s_waitcnt lgkmcnt(4)
	v_mfma_f32_32x32x16_f16 v[0:15], v[64:67], v[0:3], 0
	s_waitcnt lgkmcnt(0)
	v_mfma_f32_32x32x16_f16 v[0:15], v[80:83], v[38:41], v[0:15]
	v_and_b32_e32 v38, 15, v43
	v_mul_lo_u32 v40, v46, s86
	v_mad_i32_i24 v39, v44, s85, v45
	v_or_b32_e32 v40, v40, v38
	v_mul_f32_e32 v41, v16, v173
	v_mul_f32_e32 v45, v16, v174
	v_fma_f32 v41, -v17, v174, v41
	v_fma_f32 v45, v17, v173, v45
	v_lshl_add_u32 v40, v40, 2, v39
	s_nop 2
	v_cvt_pk_f16_f32 v16, v41, v45
	v_mul_f32_e32 v17, v18, v175
	v_mul_f32_e32 v41, v18, v176
	v_fma_f32 v17, -v19, v176, v17
	v_fma_f32 v41, v19, v175, v41
	v_add_u32_e32 v18, 0x8800, v40
	v_cvt_pk_f16_f32 v17, v17, v41
	ds_write2_b32 v18, v16, v17 offset1:17
	v_mul_f32_e32 v16, v20, v177
	v_mul_f32_e32 v17, v20, v178
	v_fma_f32 v16, -v21, v178, v16
	v_fma_f32 v17, v21, v177, v17
	v_ashrrev_i32_e32 v45, 8, v43
	v_cvt_pk_f16_f32 v16, v16, v17
	v_mul_f32_e32 v17, v22, v179
	v_mul_f32_e32 v19, v22, v180
	v_fma_f32 v17, -v23, v180, v17
	v_fma_f32 v19, v23, v179, v19
	v_and_b32_e32 v20, 0xdf, v43
	v_cvt_pk_f16_f32 v17, v17, v19
	ds_write2_b32 v18, v16, v17 offset0:68 offset1:85
	v_mul_f32_e32 v16, v24, v181
	v_mul_f32_e32 v17, v24, v182
	v_fma_f32 v16, -v25, v182, v16
	v_fma_f32 v17, v25, v181, v17
	v_mad_i32_i24 v43, v45, s87, 0
	v_cvt_pk_f16_f32 v16, v16, v17
	v_mul_f32_e32 v17, v26, v183
	v_mul_f32_e32 v19, v26, v184
	v_fma_f32 v17, -v27, v184, v17
	v_fma_f32 v19, v27, v183, v19
	v_mad_u32_u24 v21, v44, s84, v43
	v_cvt_pk_f16_f32 v17, v17, v19
	ds_write2_b32 v18, v16, v17 offset0:136 offset1:153
	v_mul_f32_e32 v16, v28, v185
	v_mul_f32_e32 v17, v28, v186
	v_fma_f32 v16, -v29, v186, v16
	v_fma_f32 v17, v29, v185, v17
	s_nop 0
	v_cvt_pk_f16_f32 v16, v16, v17
	v_mul_f32_e32 v17, v30, v187
	v_mul_f32_e32 v19, v30, v188
	v_fma_f32 v17, -v31, v188, v17
	v_fma_f32 v19, v31, v187, v19
	s_nop 0
	v_cvt_pk_f16_f32 v17, v17, v19
	ds_write2_b32 v18, v16, v17 offset0:204 offset1:221
	v_mul_lo_u32 v16, v47, s86
	v_or_b32_e32 v16, v16, v38
	s_nop 15
	s_nop 3
	v_lshl_add_u32 v16, v16, 2, v39
	v_mul_f32_e32 v17, v0, v189
	v_mul_f32_e32 v18, v0, v190
	v_fma_f32 v17, -v1, v190, v17
	v_fma_f32 v18, v1, v189, v18
	s_nop 0
	v_cvt_pk_f16_f32 v0, v17, v18
	v_mul_f32_e32 v1, v2, v191
	v_mul_f32_e32 v17, v2, v192
	v_fma_f32 v1, -v3, v192, v1
	v_fma_f32 v17, v3, v191, v17
	v_add_u32_e32 v2, 0x8800, v16
	v_cvt_pk_f16_f32 v1, v1, v17
	ds_write2_b32 v2, v0, v1 offset1:17
	v_mul_f32_e32 v0, v4, v193
	v_mul_f32_e32 v1, v4, v194
	v_fma_f32 v0, -v5, v194, v0
	v_fma_f32 v1, v5, v193, v1
	s_nop 0
	v_cvt_pk_f16_f32 v0, v0, v1
	v_mul_f32_e32 v1, v6, v195
	v_mul_f32_e32 v3, v6, v196
	v_fma_f32 v1, -v7, v196, v1
	v_fma_f32 v3, v7, v195, v3
	s_nop 0
	v_cvt_pk_f16_f32 v1, v1, v3
	ds_write2_b32 v2, v0, v1 offset0:68 offset1:85
	v_mul_f32_e32 v0, v8, v197
	v_mul_f32_e32 v1, v8, v198
	v_fma_f32 v0, -v9, v198, v0
	v_fma_f32 v1, v9, v197, v1
	s_nop 0
	v_cvt_pk_f16_f32 v0, v0, v1
	v_mul_f32_e32 v1, v10, v199
	v_mul_f32_e32 v3, v10, v200
	v_fma_f32 v1, -v11, v200, v1
	v_fma_f32 v3, v11, v199, v3
	s_nop 0
	v_cvt_pk_f16_f32 v1, v1, v3
	ds_write2_b32 v2, v0, v1 offset0:136 offset1:153
	v_mul_f32_e32 v0, v12, v201
	v_mul_f32_e32 v1, v12, v202
	v_fma_f32 v0, -v13, v202, v0
	v_fma_f32 v1, v13, v201, v1
	s_nop 0
	v_cvt_pk_f16_f32 v0, v0, v1
	v_mul_f32_e32 v1, v14, v203
	v_mul_f32_e32 v3, v14, v204
	v_fma_f32 v1, -v15, v204, v1
	v_fma_f32 v3, v15, v203, v3
	s_nop 0
	v_cvt_pk_f16_f32 v1, v1, v3
	ds_write2_b32 v2, v0, v1 offset0:204 offset1:221
	v_lshrrev_b32_e32 v0, 4, v20
	v_add_lshl_u32 v46, v0, v20, 2
	v_add_u32_e32 v17, v21, v46
	s_waitcnt lgkmcnt(0)
	s_barrier
	ds_read_b32 v0, v17 offset:34816
	ds_read_b32 v1, v17 offset:36992
	ds_read_b32 v2, v17 offset:39168
	ds_read_b32 v3, v17 offset:41344
	ds_read_b32 v18, v17 offset:56576
	ds_read_b32 v19, v17 offset:58752
	ds_read_b32 v16, v17 offset:52224
	s_waitcnt lgkmcnt(3)
	v_mfma_f32_32x32x16_f16 v[0:15], v[76:79], v[0:3], 0
	ds_read_b32 v17, v17 offset:54400
	v_or_b32_e32 v20, 32, v20
	v_lshrrev_b32_e32 v22, 4, v20
	v_add_lshl_u32 v47, v22, v20, 2
	v_add_u32_e32 v39, v21, v47
	s_waitcnt lgkmcnt(0)
	v_mfma_f32_32x32x16_f16 v[0:15], v[92:95], v[16:19], v[0:15]
	ds_read_b32 v16, v39 offset:34816
	ds_read_b32 v17, v39 offset:36992
	ds_read_b32 v18, v39 offset:39168
	ds_read_b32 v19, v39 offset:41344
	ds_read_b32 v40, v39 offset:56576
	ds_read_b32 v41, v39 offset:58752
	ds_read_b32 v38, v39 offset:52224
	ds_read_b32 v39, v39 offset:54400
	s_nop 3
	v_cvt_pk_f16_f32 v0, v0, v1
	s_waitcnt lgkmcnt(4)
	v_mfma_f32_32x32x16_f16 v[16:31], v[76:79], v[16:19], 0
	s_waitcnt lgkmcnt(0)
	v_mfma_f32_32x32x16_f16 v[16:31], v[92:95], v[38:41], v[16:31]
	v_mul_i32_i24_e32 v38, 0x3fc0, v45
	v_mul_u32_u24_e32 v39, 0x880, v44
	v_add3_u32 v38, v43, v38, v39
	v_add_u32_e32 v39, v38, v46
	ds_write_b32 v39, v0
	v_cvt_pk_f16_f32 v0, v2, v3
	ds_write_b32 v39, v0 offset:1088
	v_cvt_pk_f16_f32 v0, v4, v5
	ds_write_b32 v39, v0 offset:4352
	v_cvt_pk_f16_f32 v0, v6, v7
	ds_write_b32 v39, v0 offset:5440
	v_cvt_pk_f16_f32 v0, v8, v9
	ds_write_b32 v39, v0 offset:8704
	v_cvt_pk_f16_f32 v0, v10, v11
	ds_write_b32 v39, v0 offset:9792
	v_cvt_pk_f16_f32 v0, v12, v13
	ds_write_b32 v39, v0 offset:13056
	v_cvt_pk_f16_f32 v0, v14, v15
	ds_write_b32 v39, v0 offset:14144
	v_add_u32_e32 v0, v38, v47
	v_cvt_pk_f16_f32 v1, v16, v17
	ds_write_b32 v0, v1
	v_cvt_pk_f16_f32 v1, v18, v19
	ds_write_b32 v0, v1 offset:1088
	v_cvt_pk_f16_f32 v1, v20, v21
	ds_write_b32 v0, v1 offset:4352
	v_cvt_pk_f16_f32 v1, v22, v23
	ds_write_b32 v0, v1 offset:5440
	v_cvt_pk_f16_f32 v1, v24, v25
	ds_write_b32 v0, v1 offset:8704
	v_cvt_pk_f16_f32 v1, v26, v27
	ds_write_b32 v0, v1 offset:9792
	v_cvt_pk_f16_f32 v1, v28, v29
	ds_write_b32 v0, v1 offset:13056
	v_cvt_pk_f16_f32 v1, v30, v31
	ds_write_b32 v0, v1 offset:14144
	v_ashrrev_i32_e32 v1, 4, v37
	v_mul_u32_u24_e32 v0, 0x2200, v36
	v_add_lshl_u32 v1, v1, v37, 2
	v_add3_u32 v1, 0, v1, v0
	s_waitcnt lgkmcnt(0)
	s_barrier
	ds_read_b32 v2, v1
	ds_read_b32 v3, v1 offset:17408
	ds_read_b32 v4, v1 offset:2176
	ds_read_b32 v5, v1 offset:19584
	ds_read_b32 v6, v1 offset:4352
	ds_read_b32 v7, v1 offset:21760
	ds_read_b32 v8, v1 offset:23936
	ds_read_b32 v1, v1 offset:6528
	s_waitcnt lgkmcnt(7)
	v_cvt_f32_f16_e32 v9, v2
	s_waitcnt lgkmcnt(6)
	v_cvt_f32_f16_e32 v10, v3
	v_cvt_f32_f16_sdwa v2, v2 dst_sel:DWORD dst_unused:UNUSED_PAD src0_sel:WORD_1
	v_cvt_f32_f16_sdwa v3, v3 dst_sel:DWORD dst_unused:UNUSED_PAD src0_sel:WORD_1
	v_mov_b32_e32 v14, s4
	v_add_f32_e32 v11, v9, v10
	v_sub_f32_e32 v9, v9, v10
	v_mul_f32_e32 v210, 0x3c000000, v11
	v_add_f32_e32 v11, v2, v3
	v_mul_f32_e32 v212, 0x3c000000, v9
	v_sub_f32_e32 v2, v2, v3
	s_waitcnt lgkmcnt(5)
	v_cvt_f32_f16_e32 v3, v4
	s_waitcnt lgkmcnt(4)
	v_cvt_f32_f16_e32 v9, v5
	v_cvt_f32_f16_sdwa v4, v4 dst_sel:DWORD dst_unused:UNUSED_PAD src0_sel:WORD_1
	v_cvt_f32_f16_sdwa v5, v5 dst_sel:DWORD dst_unused:UNUSED_PAD src0_sel:WORD_1
	s_add_i32 s4, s91, s45
	v_mul_f32_e32 v213, 0x3c000000, v2
	v_add_f32_e32 v2, v3, v9
	s_ashr_i32 s5, s4, 31
	v_mul_f32_e32 v214, 0x3c000000, v2
	v_add_f32_e32 v2, v4, v5
	s_lshl_b64 s[4:5], s[4:5], 2
	v_mul_f32_e32 v215, 0x3c000000, v2
	v_sub_f32_e32 v2, v3, v9
	s_add_u32 s4, s36, s4
	v_mul_f32_e32 v216, 0x3c000000, v2
	v_sub_f32_e32 v2, v4, v5
	s_addc_u32 s5, s37, s5
	s_add_i32 s6, s90, 0x1800
	v_mul_f32_e32 v217, 0x3c000000, v2
	s_waitcnt lgkmcnt(3)
	v_cvt_f32_f16_e32 v2, v6
	v_cvt_f32_f16_sdwa v3, v6 dst_sel:DWORD dst_unused:UNUSED_PAD src0_sel:WORD_1
	v_ashrrev_i32_e32 v6, 4, v42
	s_ashr_i32 s7, s6, 31
	v_add_lshl_u32 v6, v6, v42, 2
	s_lshl_b64 s[6:7], s[6:7], 2
	v_add3_u32 v0, 0, v6, v0
	s_add_u32 s6, s36, s6
	v_mul_f32_e32 v211, 0x3c000000, v11
	s_waitcnt lgkmcnt(2)
	v_cvt_f32_f16_e32 v4, v7
	v_cvt_f32_f16_sdwa v5, v7 dst_sel:DWORD dst_unused:UNUSED_PAD src0_sel:WORD_1
	ds_read_b32 v6, v0
	ds_read_b32 v7, v0 offset:17408
	ds_read_b32 v9, v0 offset:2176
	ds_read_b32 v10, v0 offset:19584
	ds_read_b32 v11, v0 offset:4352
	ds_read_b32 v12, v0 offset:21760
	ds_read_b32 v13, v0 offset:23936
	ds_read_b32 v0, v0 offset:6528
	s_waitcnt lgkmcnt(0)
	s_barrier
	s_addc_u32 s7, s37, s7
	global_load_dword v150, v14, s[46:47]
	global_load_dword v152, v14, s[48:49]
	global_load_dword v154, v172, s[0:1]
	global_load_dword v156, v172, s[4:5]
	global_load_dword v158, v172, s[6:7]
	v_add_f32_e32 v14, v2, v4
	v_sub_f32_e32 v2, v2, v4
	v_mul_f32_e32 v218, 0x3c000000, v14
	v_add_f32_e32 v14, v3, v5
	v_mul_f32_e32 v220, 0x3c000000, v2
	v_sub_f32_e32 v2, v3, v5
	v_cvt_f32_f16_e32 v3, v1
	v_cvt_f32_f16_e32 v4, v8
	v_cvt_f32_f16_sdwa v1, v1 dst_sel:DWORD dst_unused:UNUSED_PAD src0_sel:WORD_1
	v_cvt_f32_f16_sdwa v5, v8 dst_sel:DWORD dst_unused:UNUSED_PAD src0_sel:WORD_1
	v_mul_f32_e32 v221, 0x3c000000, v2
	v_add_f32_e32 v2, v3, v4
	v_mul_f32_e32 v222, 0x3c000000, v2
	v_add_f32_e32 v2, v1, v5
	v_mul_f32_e32 v223, 0x3c000000, v2
	v_sub_f32_e32 v2, v3, v4
	v_mul_f32_e32 v224, 0x3c000000, v2
	v_cvt_f32_f16_e32 v2, v6
	v_cvt_f32_f16_e32 v3, v7
	v_sub_f32_e32 v1, v1, v5
	v_cvt_f32_f16_sdwa v4, v6 dst_sel:DWORD dst_unused:UNUSED_PAD src0_sel:WORD_1
	v_cvt_f32_f16_sdwa v5, v7 dst_sel:DWORD dst_unused:UNUSED_PAD src0_sel:WORD_1
	v_mul_f32_e32 v225, 0x3c000000, v1
	v_add_f32_e32 v1, v2, v3
	v_mul_f32_e32 v226, 0x3c000000, v1
	v_add_f32_e32 v1, v4, v5
	v_mul_f32_e32 v227, 0x3c000000, v1
	v_sub_f32_e32 v1, v2, v3
	v_cvt_f32_f16_e32 v2, v9
	v_cvt_f32_f16_e32 v3, v10
	v_mul_f32_e32 v228, 0x3c000000, v1
	v_sub_f32_e32 v1, v4, v5
	v_cvt_f32_f16_sdwa v4, v9 dst_sel:DWORD dst_unused:UNUSED_PAD src0_sel:WORD_1
	v_cvt_f32_f16_sdwa v5, v10 dst_sel:DWORD dst_unused:UNUSED_PAD src0_sel:WORD_1
	v_mul_f32_e32 v229, 0x3c000000, v1
	v_add_f32_e32 v1, v2, v3
	v_mul_f32_e32 v230, 0x3c000000, v1
	v_add_f32_e32 v1, v4, v5
	v_mul_f32_e32 v231, 0x3c000000, v1
	v_sub_f32_e32 v1, v2, v3
	v_cvt_f32_f16_e32 v2, v11
	v_cvt_f32_f16_e32 v3, v12
	v_mul_f32_e32 v232, 0x3c000000, v1
	v_sub_f32_e32 v1, v4, v5
	v_cvt_f32_f16_sdwa v4, v11 dst_sel:DWORD dst_unused:UNUSED_PAD src0_sel:WORD_1
	v_cvt_f32_f16_sdwa v5, v12 dst_sel:DWORD dst_unused:UNUSED_PAD src0_sel:WORD_1
	v_mul_f32_e32 v233, 0x3c000000, v1
	v_add_f32_e32 v1, v2, v3
	v_mul_f32_e32 v234, 0x3c000000, v1
	v_add_f32_e32 v1, v4, v5
	v_mul_f32_e32 v235, 0x3c000000, v1
	v_sub_f32_e32 v1, v2, v3
	v_cvt_f32_f16_e32 v2, v0
	v_cvt_f32_f16_e32 v3, v13
	v_mul_f32_e32 v236, 0x3c000000, v1
	v_sub_f32_e32 v1, v4, v5
	v_cvt_f32_f16_sdwa v0, v0 dst_sel:DWORD dst_unused:UNUSED_PAD src0_sel:WORD_1
	v_cvt_f32_f16_sdwa v4, v13 dst_sel:DWORD dst_unused:UNUSED_PAD src0_sel:WORD_1
	v_mul_f32_e32 v237, 0x3c000000, v1
	v_add_f32_e32 v1, v2, v3
	v_mul_f32_e32 v238, 0x3c000000, v1
	v_add_f32_e32 v1, v0, v4
	v_mul_f32_e32 v239, 0x3c000000, v1
	v_sub_f32_e32 v1, v2, v3
	v_sub_f32_e32 v0, v0, v4
	v_mul_f32_e32 v240, 0x3c000000, v1
	v_mul_f32_e32 v241, 0x3c000000, v0
	v_lshlrev_b64 v[0:1], 1, v[32:33]
	v_mul_f32_e32 v219, 0x3c000000, v14
	v_cmp_lt_i32_e64 s[0:1], 0, v209
	v_cmp_gt_i32_e64 s[4:5], s63, v209
	v_lshl_add_u64 v[160:161], s[12:13], 0, v[0:1]
	v_lshl_add_u64 v[162:163], s[14:15], 0, v[0:1]
	s_add_i32 s91, s91, s50
	s_waitcnt vmcnt(4)
	v_mov_b32_e32 v151, v150
	s_waitcnt vmcnt(3)
	v_mov_b32_e32 v153, v152
	s_waitcnt vmcnt(2)
	v_mov_b32_e32 v155, v154
	s_waitcnt vmcnt(1)
	v_mov_b32_e32 v157, v156
	s_waitcnt vmcnt(0)
	v_mov_b32_e32 v159, v158
	v_mov_b32_e32 v168, v156
	v_mov_b32_e32 v169, v150
	v_mov_b32_e32 v170, v150
	v_mov_b32_e32 v171, v156

.LBB0_1796:
	v_lshl_add_u32 v242, v209, 5, 0
	v_add_u32_e32 v0, 0x19800, v242
	ds_write_b128 v242, v[108:111] offset:34816
	ds_write_b128 v242, v[100:103] offset:34832
	ds_write_b128 v0, v[104:107]
	v_add_u32_e32 v0, 0x19810, v242
	v_bfe_u32 v129, v209, 5, 1
	v_lshlrev_b32_e32 v5, 2, v209
	ds_write_b128 v0, v[96:99]
	v_lshlrev_b32_e32 v4, 13, v129
	v_and_b32_e32 v0, 0xffffff7c, v5
	v_add_u32_e32 v6, v4, v0
	v_add_u32_e32 v2, 0, v6
	s_waitcnt lgkmcnt(0)
	s_barrier
	ds_read2st64_b32 v[0:1], v2 offset0:136 offset1:144
	ds_read2st64_b32 v[2:3], v2 offset0:152 offset1:160
	v_or_b32_e32 v5, 0x80, v5
	v_add_u32_e32 v4, v4, v5
	s_waitcnt lgkmcnt(0)
	v_mfma_f32_32x32x16_f16 v[48:63], v[68:71], v[0:3], 0
	v_add_u32_e32 v2, 0, v4
	ds_read2st64_b32 v[0:1], v2 offset0:136 offset1:144
	ds_read2st64_b32 v[2:3], v2 offset0:152 offset1:160
	s_add_i32 s6, 0, 0x19800
	v_lshrrev_b32_e32 v112, 2, v209
	v_and_b32_e32 v112, 8, v112
	v_or_b32_e32 v128, 32, v209
	v_add_u32_e32 v247, 0, v112
	s_waitcnt lgkmcnt(0)
	v_mfma_f32_32x32x16_f16 v[32:47], v[72:75], v[0:3], 0
	v_add_u32_e32 v2, s6, v6
	ds_read2st64_b32 v[0:1], v2 offset1:8
	ds_read2st64_b32 v[2:3], v2 offset0:16 offset1:24
	v_mul_lo_u32 v249, v128, s83
	v_add_u32_e32 v250, v247, v249
	v_and_b32_e32 v130, 0xffffffdf, v209
	v_mul_lo_u32 v248, v130, s83
	v_add_u32_e32 v251, v247, v248
	s_waitcnt lgkmcnt(0)
	v_mfma_f32_32x32x16_f16 v[16:31], v[68:71], v[0:3], 0
	v_add_u32_e32 v2, s6, v4
	ds_read2st64_b32 v[0:1], v2 offset1:8
	ds_read2st64_b32 v[2:3], v2 offset0:16 offset1:24
	v_cvt_pk_f16_f32 v32, v32, v33
	v_cvt_pk_f16_f32 v33, v34, v35
	ds_write2_b32 v250, v32, v33 offset1:1
	v_cvt_pk_f16_f32 v32, v36, v37
	v_cvt_pk_f16_f32 v33, v38, v39
	s_waitcnt lgkmcnt(1)
	v_mfma_f32_32x32x16_f16 v[0:15], v[72:75], v[0:3], 0
	ds_write2_b32 v250, v32, v33 offset0:4 offset1:5
	v_cvt_pk_f16_f32 v32, v40, v41
	v_cvt_pk_f16_f32 v33, v42, v43
	ds_write2_b32 v250, v32, v33 offset0:8 offset1:9
	v_cvt_pk_f16_f32 v32, v44, v45
	v_cvt_pk_f16_f32 v33, v46, v47
	ds_write2_b32 v250, v32, v33 offset0:12 offset1:13
	v_add_u32_e32 v32, 0x11000, v247
	v_add_u32_e32 v33, v32, v248
	v_cvt_pk_f16_f32 v16, v16, v17
	v_cvt_pk_f16_f32 v17, v18, v19
	ds_write2_b32 v33, v16, v17 offset1:1
	v_cvt_pk_f16_f32 v16, v20, v21
	v_cvt_pk_f16_f32 v17, v22, v23
	ds_write2_b32 v33, v16, v17 offset0:4 offset1:5
	v_cvt_pk_f16_f32 v16, v24, v25
	v_cvt_pk_f16_f32 v17, v26, v27
	ds_write2_b32 v33, v16, v17 offset0:8 offset1:9
	v_cvt_pk_f16_f32 v16, v28, v29
	v_cvt_pk_f16_f32 v17, v30, v31
	v_cvt_pk_f16_f32 v48, v48, v49
	v_cvt_pk_f16_f32 v49, v50, v51
	ds_write2_b32 v33, v16, v17 offset0:12 offset1:13
	v_add_u32_e32 v16, v32, v249
	v_cvt_pk_f16_f32 v0, v0, v1
	v_cvt_pk_f16_f32 v1, v2, v3
	ds_write2_b32 v251, v48, v49 offset1:1
	v_cvt_pk_f16_f32 v48, v52, v53
	v_cvt_pk_f16_f32 v49, v54, v55
	ds_write2_b32 v16, v0, v1 offset1:1
	v_cvt_pk_f16_f32 v0, v4, v5
	v_cvt_pk_f16_f32 v1, v6, v7
	ds_write2_b32 v251, v48, v49 offset0:4 offset1:5
	v_cvt_pk_f16_f32 v48, v56, v57
	v_cvt_pk_f16_f32 v49, v58, v59
	ds_write2_b32 v16, v0, v1 offset0:4 offset1:5
	v_cvt_pk_f16_f32 v0, v8, v9
	v_cvt_pk_f16_f32 v1, v10, v11
	ds_write2_b32 v251, v48, v49 offset0:8 offset1:9
	v_cvt_pk_f16_f32 v48, v60, v61
	v_cvt_pk_f16_f32 v49, v62, v63
	ds_write2_b32 v16, v0, v1 offset0:8 offset1:9
	v_cvt_pk_f16_f32 v0, v12, v13
	v_cvt_pk_f16_f32 v1, v14, v15
	v_mov_b32_e32 v116, v209
	ds_write2_b32 v251, v48, v49 offset0:12 offset1:13
	ds_write2_b32 v16, v0, v1 offset0:12 offset1:13
	s_waitcnt lgkmcnt(0)
	s_barrier
	s_lshl_b32 s8, s60, 14
	v_and_b32_e32 v0, 0xffffffdf, v116
	v_bfe_u32 v117, v116, 5, 1
	v_ashrrev_i32_e32 v119, 4, v0
	v_mad_u32_u24 v118, v117, s84, 0
	v_add_lshl_u32 v8, v119, v0, 2
	v_add_u32_e32 v5, v118, v8
	ds_read_b32 v0, v5
	ds_read_b32 v1, v5 offset:2176
	ds_read_b32 v2, v5 offset:4352
	ds_read_b32 v3, v5 offset:6528
	ds_read_b32 v6, v5 offset:21760
	ds_read_b32 v7, v5 offset:23936
	ds_read_b32 v4, v5 offset:17408
	s_waitcnt lgkmcnt(3)
	v_mfma_f32_32x32x16_f16 v[48:63], v[64:67], v[0:3], 0
	ds_read_b32 v5, v5 offset:19584
	v_or_b32_e32 v0, 32, v116
	v_ashrrev_i32_e32 v120, 4, v0
	v_add_lshl_u32 v9, v120, v0, 2
	v_add_u32_e32 v10, v118, v9
	s_add_i32 s6, s8, s90
	s_ashr_i32 s7, s6, 31
	s_waitcnt lgkmcnt(0)
	v_mfma_f32_32x32x16_f16 v[48:63], v[80:83], v[4:7], v[48:63]
	ds_read_b32 v0, v10
	ds_read_b32 v1, v10 offset:2176
	ds_read_b32 v2, v10 offset:4352
	ds_read_b32 v3, v10 offset:6528
	ds_read_b32 v6, v10 offset:21760
	ds_read_b32 v7, v10 offset:23936
	ds_read_b32 v4, v10 offset:17408
	ds_read_b32 v5, v10 offset:19584
	v_add_u32_e32 v10, 0x11000, v118
	v_add_u32_e32 v8, v10, v8
	v_add_u32_e32 v113, v10, v9
	s_lshl_b64 s[6:7], s[6:7], 13
	s_andn2_b64 vcc, exec, s[52:53]
	s_waitcnt lgkmcnt(4)
	v_mfma_f32_32x32x16_f16 v[32:47], v[64:67], v[0:3], 0
	v_mov_b32_e32 v122, 0
	v_mov_b32_e32 v123, 0
	s_waitcnt lgkmcnt(0)
	v_mfma_f32_32x32x16_f16 v[32:47], v[80:83], v[4:7], v[32:47]
	ds_read_b32 v0, v8
	ds_read_b32 v1, v8 offset:2176
	ds_read_b32 v2, v8 offset:4352
	ds_read_b32 v3, v8 offset:6528
	ds_read_b32 v6, v8 offset:21760
	ds_read_b32 v7, v8 offset:23936
	ds_read_b32 v4, v8 offset:17408
	ds_read_b32 v5, v8 offset:19584
	s_waitcnt lgkmcnt(4)
	v_mfma_f32_32x32x16_f16 v[16:31], v[64:67], v[0:3], 0
	ds_read_b32 v0, v113
	ds_read_b32 v1, v113 offset:2176
	ds_read_b32 v2, v113 offset:4352
	ds_read_b32 v3, v113 offset:6528
	ds_read_b32 v114, v113 offset:21760
	ds_read_b32 v115, v113 offset:23936
	ds_read_b32 v112, v113 offset:17408
	ds_read_b32 v113, v113 offset:19584
	s_nop 15
	s_nop 3
	s_waitcnt lgkmcnt(8)
	v_mfma_f32_32x32x16_f16 v[16:31], v[80:83], v[4:7], v[16:31]
	s_waitcnt lgkmcnt(4)
	v_mfma_f32_32x32x16_f16 v[0:15], v[64:67], v[0:3], 0
	s_waitcnt lgkmcnt(0)
	v_mfma_f32_32x32x16_f16 v[0:15], v[80:83], v[112:115], v[0:15]
	v_and_b32_e32 v112, 15, v116
	v_mul_lo_u32 v114, v119, s86
	v_or_b32_e32 v114, v114, v112
	v_mad_i32_i24 v113, v117, s85, v118
	v_lshlrev_b32_e32 v114, 2, v114
	v_mul_f32_e32 v119, v48, v173
	v_mul_f32_e32 v121, v48, v174
	v_fma_f32 v119, -v49, v174, v119
	v_fma_f32 v121, v49, v173, v121
	v_add_u32_e32 v115, v113, v114
	v_cvt_pk_f16_f32 v48, v119, v121
	v_mul_f32_e32 v49, v50, v175
	v_mul_f32_e32 v119, v50, v176
	v_fma_f32 v49, -v51, v176, v49
	v_fma_f32 v119, v51, v175, v119
	v_add_u32_e32 v50, 0x8800, v115
	v_cvt_pk_f16_f32 v49, v49, v119
	ds_write2_b32 v50, v48, v49 offset1:17
	v_mul_f32_e32 v48, v52, v177
	v_mul_f32_e32 v49, v52, v178
	v_fma_f32 v48, -v53, v178, v48
	v_fma_f32 v49, v53, v177, v49
	v_ashrrev_i32_e32 v119, 8, v116
	v_cvt_pk_f16_f32 v48, v48, v49
	v_mul_f32_e32 v49, v54, v179
	v_mul_f32_e32 v51, v54, v180
	v_fma_f32 v49, -v55, v180, v49
	v_fma_f32 v51, v55, v179, v51
	v_mov_b32_e32 v121, 0
	v_cvt_pk_f16_f32 v49, v49, v51
	ds_write2_b32 v50, v48, v49 offset0:68 offset1:85
	v_mul_f32_e32 v48, v56, v181
	v_mul_f32_e32 v49, v56, v182
	v_fma_f32 v48, -v57, v182, v48
	v_fma_f32 v49, v57, v181, v49
	s_nop 0
	v_cvt_pk_f16_f32 v48, v48, v49
	v_mul_f32_e32 v49, v58, v183
	v_mul_f32_e32 v51, v58, v184
	v_fma_f32 v49, -v59, v184, v49
	v_fma_f32 v51, v59, v183, v51
	s_nop 0
	v_cvt_pk_f16_f32 v49, v49, v51
	ds_write2_b32 v50, v48, v49 offset0:136 offset1:153
	v_mul_f32_e32 v48, v60, v185
	v_mul_f32_e32 v49, v60, v186
	v_fma_f32 v48, -v61, v186, v48
	v_fma_f32 v49, v61, v185, v49
	s_nop 0
	v_cvt_pk_f16_f32 v48, v48, v49
	v_mul_f32_e32 v49, v62, v187
	v_mul_f32_e32 v51, v62, v188
	v_fma_f32 v49, -v63, v188, v49
	v_fma_f32 v51, v63, v187, v51
	s_nop 0
	v_cvt_pk_f16_f32 v49, v49, v51
	ds_write2_b32 v50, v48, v49 offset0:204 offset1:221
	v_mul_lo_u32 v48, v120, s86
	v_or_b32_e32 v48, v48, v112
	v_lshlrev_b32_e32 v48, 2, v48
	s_nop 15
	s_nop 3
	v_add_u32_e32 v49, v113, v48
	v_mul_f32_e32 v50, v32, v189
	v_mul_f32_e32 v51, v32, v190
	v_fma_f32 v50, -v33, v190, v50
	v_fma_f32 v51, v33, v189, v51
	v_mov_b32_e32 v120, 0
	v_cvt_pk_f16_f32 v32, v50, v51
	v_mul_f32_e32 v33, v34, v191
	v_mul_f32_e32 v50, v34, v192
	v_fma_f32 v33, -v35, v192, v33
	v_fma_f32 v50, v35, v191, v50
	v_add_u32_e32 v34, 0x8800, v49
	v_cvt_pk_f16_f32 v33, v33, v50
	ds_write2_b32 v34, v32, v33 offset1:17
	v_mul_f32_e32 v32, v36, v193
	v_mul_f32_e32 v33, v36, v194
	v_fma_f32 v32, -v37, v194, v32
	v_fma_f32 v33, v37, v193, v33
	s_nop 0
	v_cvt_pk_f16_f32 v32, v32, v33
	v_mul_f32_e32 v33, v38, v195
	v_mul_f32_e32 v35, v38, v196
	v_fma_f32 v33, -v39, v196, v33
	v_fma_f32 v35, v39, v195, v35
	s_nop 0
	v_cvt_pk_f16_f32 v33, v33, v35
	ds_write2_b32 v34, v32, v33 offset0:68 offset1:85
	v_mul_f32_e32 v32, v40, v197
	v_mul_f32_e32 v33, v40, v198
	v_fma_f32 v32, -v41, v198, v32
	v_fma_f32 v33, v41, v197, v33
	s_nop 0
	v_cvt_pk_f16_f32 v32, v32, v33
	v_mul_f32_e32 v33, v42, v199
	v_mul_f32_e32 v35, v42, v200
	v_fma_f32 v33, -v43, v200, v33
	v_fma_f32 v35, v43, v199, v35
	s_nop 0
	v_cvt_pk_f16_f32 v33, v33, v35
	ds_write2_b32 v34, v32, v33 offset0:136 offset1:153
	v_mul_f32_e32 v32, v44, v201
	v_mul_f32_e32 v33, v44, v202
	v_fma_f32 v32, -v45, v202, v32
	v_fma_f32 v33, v45, v201, v33
	s_nop 0
	v_cvt_pk_f16_f32 v32, v32, v33
	v_mul_f32_e32 v33, v46, v203
	v_mul_f32_e32 v35, v46, v204
	v_fma_f32 v33, -v47, v204, v33
	v_fma_f32 v35, v47, v203, v35
	s_nop 0
	v_cvt_pk_f16_f32 v33, v33, v35
	ds_write2_b32 v34, v32, v33 offset0:204 offset1:221
	s_nop 15
	s_nop 3
	v_add_u32_e32 v32, 0x19800, v113
	v_mul_f32_e32 v34, v16, v173
	v_mul_f32_e32 v35, v16, v174
	v_fma_f32 v34, -v17, v174, v34
	v_fma_f32 v35, v17, v173, v35
	v_add_u32_e32 v33, v32, v114
	v_cvt_pk_f16_f32 v16, v34, v35
	v_mul_f32_e32 v17, v18, v175
	v_mul_f32_e32 v34, v18, v176
	v_fma_f32 v17, -v19, v176, v17
	v_fma_f32 v34, v19, v175, v34
	s_nop 0
	v_cvt_pk_f16_f32 v17, v17, v34
	ds_write2_b32 v33, v16, v17 offset1:17
	v_mul_f32_e32 v16, v20, v177
	v_mul_f32_e32 v17, v20, v178
	v_fma_f32 v16, -v21, v178, v16
	v_fma_f32 v17, v21, v177, v17
	v_and_b32_e32 v20, 0xdf, v116
	v_cvt_pk_f16_f32 v16, v16, v17
	v_mul_f32_e32 v17, v22, v179
	v_mul_f32_e32 v18, v22, v180
	v_fma_f32 v17, -v23, v180, v17
	v_fma_f32 v18, v23, v179, v18
	s_nop 0
	v_cvt_pk_f16_f32 v17, v17, v18
	ds_write2_b32 v33, v16, v17 offset0:68 offset1:85
	v_mul_f32_e32 v16, v24, v181
	v_mul_f32_e32 v17, v24, v182
	v_fma_f32 v16, -v25, v182, v16
	v_fma_f32 v17, v25, v181, v17
	v_mad_i32_i24 v24, v119, s87, v118
	v_cvt_pk_f16_f32 v16, v16, v17
	v_mul_f32_e32 v17, v26, v183
	v_mul_f32_e32 v18, v26, v184
	v_fma_f32 v17, -v27, v184, v17
	v_fma_f32 v18, v27, v183, v18
	s_nop 0
	v_cvt_pk_f16_f32 v17, v17, v18
	ds_write2_b32 v33, v16, v17 offset0:136 offset1:153
	v_mul_f32_e32 v16, v28, v185
	v_mul_f32_e32 v17, v28, v186
	v_fma_f32 v16, -v29, v186, v16
	v_fma_f32 v17, v29, v185, v17
	s_nop 0
	v_cvt_pk_f16_f32 v16, v16, v17
	v_mul_f32_e32 v17, v30, v187
	v_mul_f32_e32 v18, v30, v188
	v_fma_f32 v17, -v31, v188, v17
	v_fma_f32 v18, v31, v187, v18
	s_nop 0
	v_cvt_pk_f16_f32 v17, v17, v18
	ds_write2_b32 v33, v16, v17 offset0:204 offset1:221
	s_nop 15
	s_nop 3
	v_add_u32_e32 v16, v32, v48
	v_mul_f32_e32 v17, v0, v189
	v_mul_f32_e32 v18, v0, v190
	v_fma_f32 v17, -v1, v190, v17
	v_fma_f32 v18, v1, v189, v18
	s_nop 0
	v_cvt_pk_f16_f32 v0, v17, v18
	v_mul_f32_e32 v1, v2, v191
	v_mul_f32_e32 v17, v2, v192
	v_fma_f32 v1, -v3, v192, v1
	v_fma_f32 v17, v3, v191, v17
	s_nop 0
	v_cvt_pk_f16_f32 v1, v1, v17
	ds_write2_b32 v16, v0, v1 offset1:17
	v_mul_f32_e32 v0, v4, v193
	v_mul_f32_e32 v1, v4, v194
	v_fma_f32 v0, -v5, v194, v0
	v_fma_f32 v1, v5, v193, v1
	s_nop 0
	v_cvt_pk_f16_f32 v0, v0, v1
	v_mul_f32_e32 v1, v6, v195
	v_mul_f32_e32 v2, v6, v196
	v_fma_f32 v1, -v7, v196, v1
	v_fma_f32 v2, v7, v195, v2
	s_nop 0
	v_cvt_pk_f16_f32 v1, v1, v2
	ds_write2_b32 v16, v0, v1 offset0:68 offset1:85
	v_mul_f32_e32 v0, v8, v197
	v_mul_f32_e32 v1, v8, v198
	v_fma_f32 v0, -v9, v198, v0
	v_fma_f32 v1, v9, v197, v1
	s_nop 0
	v_cvt_pk_f16_f32 v0, v0, v1
	v_mul_f32_e32 v1, v10, v199
	v_mul_f32_e32 v2, v10, v200
	v_fma_f32 v1, -v11, v200, v1
	v_fma_f32 v2, v11, v199, v2
	s_nop 0
	v_cvt_pk_f16_f32 v1, v1, v2
	ds_write2_b32 v16, v0, v1 offset0:136 offset1:153
	v_mul_f32_e32 v0, v12, v201
	v_mul_f32_e32 v1, v12, v202
	v_fma_f32 v0, -v13, v202, v0
	v_fma_f32 v1, v13, v201, v1
	s_nop 0
	v_cvt_pk_f16_f32 v0, v0, v1
	v_mul_f32_e32 v1, v14, v203
	v_mul_f32_e32 v2, v14, v204
	v_fma_f32 v1, -v15, v204, v1
	v_fma_f32 v2, v15, v203, v2
	s_nop 0
	v_cvt_pk_f16_f32 v1, v1, v2
	ds_write2_b32 v16, v0, v1 offset0:204 offset1:221
	v_lshrrev_b32_e32 v0, 4, v20
	v_add_lshl_u32 v116, v0, v20, 2
	v_add_u32_e32 v17, v24, v116
	s_waitcnt lgkmcnt(0)
	s_barrier
	ds_read_b32 v0, v17 offset:34816
	ds_read_b32 v1, v17 offset:36992
	ds_read_b32 v2, v17 offset:39168
	ds_read_b32 v3, v17 offset:41344
	ds_read_b32 v18, v17 offset:56576
	ds_read_b32 v19, v17 offset:58752
	ds_read_b32 v16, v17 offset:52224
	s_waitcnt lgkmcnt(3)
	v_mfma_f32_32x32x16_f16 v[0:15], v[76:79], v[0:3], 0
	ds_read_b32 v17, v17 offset:54400
	v_or_b32_e32 v20, 32, v20
	v_lshrrev_b32_e32 v21, 4, v20
	v_add_lshl_u32 v118, v21, v20, 2
	v_add_u32_e32 v21, v24, v118
	v_add_u32_e32 v24, 0x19800, v24
	v_add_u32_e32 v25, v24, v116
	s_waitcnt lgkmcnt(0)
	v_mfma_f32_32x32x16_f16 v[0:15], v[92:95], v[16:19], v[0:15]
	ds_read_b32 v16, v21 offset:34816
	ds_read_b32 v17, v21 offset:36992
	ds_read_b32 v18, v21 offset:39168
	ds_read_b32 v19, v21 offset:41344
	ds_read_b32 v22, v21 offset:56576
	ds_read_b32 v23, v21 offset:58752
	ds_read_b32 v20, v21 offset:52224
	ds_read_b32 v21, v21 offset:54400
	v_add_u32_e32 v113, v24, v118
	s_nop 2
	v_cvt_pk_f16_f32 v0, v0, v1
	s_waitcnt lgkmcnt(4)
	v_mfma_f32_32x32x16_f16 v[48:63], v[76:79], v[16:19], 0
	s_waitcnt lgkmcnt(0)
	v_mfma_f32_32x32x16_f16 v[48:63], v[92:95], v[20:23], v[48:63]
	ds_read_b32 v16, v25
	ds_read_b32 v17, v25 offset:2176
	ds_read_b32 v18, v25 offset:4352
	ds_read_b32 v19, v25 offset:6528
	ds_read_b32 v22, v25 offset:21760
	ds_read_b32 v23, v25 offset:23936
	ds_read_b32 v20, v25 offset:17408
	ds_read_b32 v21, v25 offset:19584
	s_nop 3
	v_cvt_pk_f16_f32 v1, v48, v49
	s_waitcnt lgkmcnt(4)
	v_mfma_f32_32x32x16_f16 v[32:47], v[76:79], v[16:19], 0
	ds_read_b32 v16, v113
	ds_read_b32 v17, v113 offset:2176
	ds_read_b32 v18, v113 offset:4352
	ds_read_b32 v19, v113 offset:6528
	ds_read_b32 v114, v113 offset:21760
	ds_read_b32 v115, v113 offset:23936
	ds_read_b32 v112, v113 offset:17408
	ds_read_b32 v113, v113 offset:19584
	s_waitcnt lgkmcnt(8)
	v_mfma_f32_32x32x16_f16 v[32:47], v[92:95], v[20:23], v[32:47]
	s_waitcnt lgkmcnt(4)
	v_mfma_f32_32x32x16_f16 v[16:31], v[76:79], v[16:19], 0
	s_waitcnt lgkmcnt(0)
	v_mfma_f32_32x32x16_f16 v[16:31], v[92:95], v[112:115], v[16:31]
	v_mul_i32_i24_e32 v112, 0x4400, v119
	v_mul_u32_u24_e32 v113, 0x880, v117
	v_add3_u32 v112, 0, v112, v113
	v_add_u32_e32 v113, v112, v116
	ds_write_b32 v113, v0
	v_cvt_pk_f16_f32 v0, v2, v3
	ds_write_b32 v113, v0 offset:1088
	v_cvt_pk_f16_f32 v0, v4, v5
	ds_write_b32 v113, v0 offset:4352
	v_cvt_pk_f16_f32 v0, v6, v7
	ds_write_b32 v113, v0 offset:5440
	v_cvt_pk_f16_f32 v0, v8, v9
	ds_write_b32 v113, v0 offset:8704
	v_cvt_pk_f16_f32 v0, v10, v11
	ds_write_b32 v113, v0 offset:9792
	v_cvt_pk_f16_f32 v0, v12, v13
	ds_write_b32 v113, v0 offset:13056
	v_cvt_pk_f16_f32 v0, v14, v15
	ds_write_b32 v113, v0 offset:14144
	v_add_u32_e32 v0, v112, v118
	ds_write_b32 v0, v1
	v_cvt_pk_f16_f32 v1, v50, v51
	ds_write_b32 v0, v1 offset:1088
	v_cvt_pk_f16_f32 v1, v52, v53
	ds_write_b32 v0, v1 offset:4352
	v_cvt_pk_f16_f32 v1, v54, v55
	ds_write_b32 v0, v1 offset:5440
	v_cvt_pk_f16_f32 v1, v56, v57
	ds_write_b32 v0, v1 offset:8704
	v_cvt_pk_f16_f32 v1, v58, v59
	ds_write_b32 v0, v1 offset:9792
	v_cvt_pk_f16_f32 v1, v60, v61
	ds_write_b32 v0, v1 offset:13056
	v_cvt_pk_f16_f32 v1, v62, v63
	ds_write_b32 v0, v1 offset:14144
	v_add_u32_e32 v0, 0x11000, v112
	v_add_u32_e32 v1, v0, v116
	v_cvt_pk_f16_f32 v2, v32, v33
	ds_write_b32 v1, v2
	v_cvt_pk_f16_f32 v2, v34, v35
	ds_write_b32 v1, v2 offset:1088
	v_cvt_pk_f16_f32 v2, v36, v37
	ds_write_b32 v1, v2 offset:4352
	v_cvt_pk_f16_f32 v2, v38, v39
	ds_write_b32 v1, v2 offset:5440
	v_cvt_pk_f16_f32 v2, v40, v41
	ds_write_b32 v1, v2 offset:8704
	v_cvt_pk_f16_f32 v2, v42, v43
	ds_write_b32 v1, v2 offset:9792
	v_cvt_pk_f16_f32 v2, v44, v45
	ds_write_b32 v1, v2 offset:13056
	v_cvt_pk_f16_f32 v2, v46, v47
	ds_write_b32 v1, v2 offset:14144
	v_add_u32_e32 v0, v0, v118
	v_cvt_pk_f16_f32 v1, v16, v17
	ds_write_b32 v0, v1
	v_cvt_pk_f16_f32 v1, v18, v19
	ds_write_b32 v0, v1 offset:1088
	v_cvt_pk_f16_f32 v1, v20, v21
	ds_write_b32 v0, v1 offset:4352
	v_cvt_pk_f16_f32 v1, v22, v23
	ds_write_b32 v0, v1 offset:5440
	v_cvt_pk_f16_f32 v1, v24, v25
	ds_write_b32 v0, v1 offset:8704
	v_cvt_pk_f16_f32 v1, v26, v27
	ds_write_b32 v0, v1 offset:9792
	v_cvt_pk_f16_f32 v1, v28, v29
	ds_write_b32 v0, v1 offset:13056
	v_cvt_pk_f16_f32 v1, v30, v31
	ds_write_b32 v0, v1 offset:14144
	v_lshl_add_u64 v[0:1], v[160:161], 0, s[6:7]
	s_waitcnt lgkmcnt(0)
	s_barrier
	global_load_dwordx4 v[124:127], v[0:1], off nt
	global_load_ushort v246, v[0:1], off offset:16 nt
	global_load_ushort v245, v[0:1], off offset:-2 nt
	v_cndmask_b32_e64 v0, 0, 1, s[52:53]
	v_mov_b32_e32 v112, 0
	v_cmp_ne_u32_e64 s[6:7], 1, v0
	s_cbranch_vccnz .LBB0_1798
	s_add_i32 s92, s8, s45
	s_ashr_i32 s93, s92, 31
	s_lshl_b64 s[92:93], s[92:93], 13
	v_lshl_add_u64 v[0:1], v[160:161], 0, s[92:93]
	global_load_dwordx4 v[120:123], v[0:1], off nt
.LBB0_1798:
	s_or_b32 s9, s8, 0x1000
	s_add_i32 s92, s9, s90
	s_ashr_i32 s93, s92, 31
	s_lshl_b64 s[92:93], s[92:93], 13
	v_lshl_add_u64 v[0:1], v[160:161], 0, s[92:93]
	global_load_dwordx4 v[116:119], v[0:1], off nt
	global_load_ushort v244, v[0:1], off offset:16 nt
	global_load_ushort v243, v[0:1], off offset:-2 nt
	s_and_b64 vcc, exec, s[6:7]
	v_mov_b32_e32 v113, 0
	v_mov_b32_e32 v114, 0
	v_mov_b32_e32 v115, 0
	s_cbranch_vccnz .LBB0_1800
	s_add_i32 s92, s9, s45
	s_ashr_i32 s93, s92, 31
	s_lshl_b64 s[92:93], s[92:93], 13
	v_lshl_add_u64 v[0:1], v[160:161], 0, s[92:93]
	global_load_dwordx4 v[112:115], v[0:1], off nt
.LBB0_1800:
	v_ashrrev_i32_e32 v0, 4, v130
	v_mul_u32_u24_e32 v4, 0x2200, v129
	v_add_lshl_u32 v6, v0, v130, 2
	v_add3_u32 v3, 0, v6, v4
	ds_read_b32 v0, v3
	ds_read_b32 v2, v3 offset:17408
	s_add_i32 s10, 0, 0x11000
	v_add3_u32 v6, s10, v6, v4
	s_add_i32 s92, s91, s8
	s_waitcnt lgkmcnt(1)
	v_cvt_f32_f16_e32 v1, v0
	v_cvt_f32_f16_sdwa v0, v0 dst_sel:DWORD dst_unused:UNUSED_PAD src0_sel:WORD_1
	s_waitcnt lgkmcnt(0)
	v_cvt_f32_f16_e32 v5, v2
	v_cvt_f32_f16_sdwa v2, v2 dst_sel:DWORD dst_unused:UNUSED_PAD src0_sel:WORD_1
	s_ashr_i32 s93, s92, 31
	s_lshl_b64 s[92:93], s[92:93], 13
	v_add_f32_e32 v7, v1, v5
	v_add_f32_e32 v8, v0, v2
	v_sub_f32_e32 v1, v1, v5
	v_sub_f32_e32 v0, v0, v2
	v_mul_f32_e32 v2, v7, v210
	v_mul_f32_e64 v5, -v7, v211
	v_fma_f32 v2, -v8, v211, v2
	v_fma_f32 v5, -v8, v210, v5
	v_mul_f32_e32 v7, v1, v212
	v_mul_f32_e64 v8, -v1, v213
	v_fma_f32 v7, -v0, v213, v7
	v_fma_f32 v8, -v0, v212, v8
	ds_read_b32 v1, v3 offset:2176
	v_cvt_pk_f16_f32 v0, v2, v5
	ds_read_b32 v5, v3 offset:19584
	v_cvt_pk_f16_f32 v16, v7, v8
	s_and_b64 vcc, exec, s[6:7]
	s_waitcnt lgkmcnt(1)
	v_cvt_f32_f16_e32 v2, v1
	v_cvt_f32_f16_sdwa v1, v1 dst_sel:DWORD dst_unused:UNUSED_PAD src0_sel:WORD_1
	s_waitcnt lgkmcnt(0)
	v_cvt_f32_f16_e32 v7, v5
	v_cvt_f32_f16_sdwa v5, v5 dst_sel:DWORD dst_unused:UNUSED_PAD src0_sel:WORD_1
	v_add_f32_e32 v8, v2, v7
	v_add_f32_e32 v9, v1, v5
	v_sub_f32_e32 v2, v2, v7
	v_sub_f32_e32 v1, v1, v5
	v_mul_f32_e32 v5, v8, v214
	v_mul_f32_e64 v7, -v8, v215
	v_fma_f32 v5, -v9, v215, v5
	v_fma_f32 v7, -v9, v214, v7
	v_mul_f32_e32 v8, v2, v216
	v_mul_f32_e64 v9, -v2, v217
	v_fma_f32 v8, -v1, v217, v8
	v_fma_f32 v9, -v1, v216, v9
	ds_read_b32 v2, v3 offset:4352
	v_cvt_pk_f16_f32 v1, v5, v7
	ds_read_b32 v7, v3 offset:21760
	v_cvt_pk_f16_f32 v17, v8, v9
	s_waitcnt lgkmcnt(1)
	v_cvt_f32_f16_e32 v5, v2
	v_cvt_f32_f16_sdwa v2, v2 dst_sel:DWORD dst_unused:UNUSED_PAD src0_sel:WORD_1
	s_waitcnt lgkmcnt(0)
	v_cvt_f32_f16_e32 v8, v7
	v_cvt_f32_f16_sdwa v7, v7 dst_sel:DWORD dst_unused:UNUSED_PAD src0_sel:WORD_1
	v_add_f32_e32 v9, v5, v8
	v_add_f32_e32 v10, v2, v7
	v_sub_f32_e32 v5, v5, v8
	v_sub_f32_e32 v2, v2, v7
	v_mul_f32_e32 v7, v9, v218
	v_mul_f32_e64 v8, -v9, v219
	v_fma_f32 v7, -v10, v219, v7
	v_fma_f32 v8, -v10, v218, v8
	v_mul_f32_e32 v9, v5, v220
	v_mul_f32_e64 v10, -v5, v221
	v_fma_f32 v9, -v2, v221, v9
	v_fma_f32 v10, -v2, v220, v10
	ds_read_b32 v5, v3 offset:6528
	ds_read_b32 v3, v3 offset:23936
	v_cvt_pk_f16_f32 v2, v7, v8
	v_cvt_pk_f16_f32 v18, v9, v10
	s_waitcnt lgkmcnt(1)
	v_cvt_f32_f16_e32 v7, v5
	v_cvt_f32_f16_sdwa v5, v5 dst_sel:DWORD dst_unused:UNUSED_PAD src0_sel:WORD_1
	s_waitcnt lgkmcnt(0)
	v_cvt_f32_f16_e32 v8, v3
	v_cvt_f32_f16_sdwa v3, v3 dst_sel:DWORD dst_unused:UNUSED_PAD src0_sel:WORD_1
	v_add_f32_e32 v9, v7, v8
	v_add_f32_e32 v10, v5, v3
	v_sub_f32_e32 v7, v7, v8
	v_sub_f32_e32 v3, v5, v3
	v_mul_f32_e32 v5, v9, v222
	v_mul_f32_e64 v8, -v9, v223
	v_fma_f32 v5, -v10, v223, v5
	v_fma_f32 v8, -v10, v222, v8
	v_mul_f32_e32 v9, v7, v224
	v_mul_f32_e64 v10, -v7, v225
	v_fma_f32 v9, -v3, v225, v9
	v_fma_f32 v10, -v3, v224, v10
	s_nop 0
	v_cvt_pk_f16_f32 v3, v5, v8
	v_ashrrev_i32_e32 v5, 4, v128
	v_add_lshl_u32 v5, v5, v128, 2
	v_add3_u32 v7, 0, v5, v4
	v_cvt_pk_f16_f32 v19, v9, v10
	ds_read_b32 v8, v7
	ds_read_b32 v10, v7 offset:17408
	v_add3_u32 v4, s10, v5, v4
	ds_read_b32 v5, v4
	s_waitcnt lgkmcnt(2)
	v_cvt_f32_f16_e32 v9, v8
	v_cvt_f32_f16_sdwa v8, v8 dst_sel:DWORD dst_unused:UNUSED_PAD src0_sel:WORD_1
	s_waitcnt lgkmcnt(1)
	v_cvt_f32_f16_e32 v11, v10
	v_cvt_f32_f16_sdwa v10, v10 dst_sel:DWORD dst_unused:UNUSED_PAD src0_sel:WORD_1
	v_add_f32_e32 v12, v9, v11
	v_add_f32_e32 v13, v8, v10
	v_sub_f32_e32 v9, v9, v11
	v_sub_f32_e32 v8, v8, v10
	v_mul_f32_e32 v10, v12, v226
	v_mul_f32_e64 v11, -v12, v227
	v_fma_f32 v10, -v13, v227, v10
	v_fma_f32 v11, -v13, v226, v11
	v_mul_f32_e32 v12, v9, v228
	v_mul_f32_e64 v13, -v9, v229
	v_fma_f32 v12, -v8, v229, v12
	v_fma_f32 v13, -v8, v228, v13
	ds_read_b32 v8, v7 offset:2176
	v_cvt_pk_f16_f32 v20, v10, v11
	ds_read_b32 v10, v7 offset:19584
	v_cvt_pk_f16_f32 v32, v12, v13
	s_waitcnt lgkmcnt(1)
	v_cvt_f32_f16_e32 v9, v8
	v_cvt_f32_f16_sdwa v8, v8 dst_sel:DWORD dst_unused:UNUSED_PAD src0_sel:WORD_1
	s_waitcnt lgkmcnt(0)
	v_cvt_f32_f16_e32 v11, v10
	v_cvt_f32_f16_sdwa v10, v10 dst_sel:DWORD dst_unused:UNUSED_PAD src0_sel:WORD_1
	v_add_f32_e32 v12, v9, v11
	v_add_f32_e32 v13, v8, v10
	v_sub_f32_e32 v9, v9, v11
	v_sub_f32_e32 v8, v8, v10
	v_mul_f32_e32 v10, v12, v230
	v_mul_f32_e64 v11, -v12, v231
	v_fma_f32 v10, -v13, v231, v10
	v_fma_f32 v11, -v13, v230, v11
	v_mul_f32_e32 v12, v9, v232
	v_mul_f32_e64 v13, -v9, v233
	v_fma_f32 v12, -v8, v233, v12
	v_fma_f32 v13, -v8, v232, v13
	ds_read_b32 v8, v7 offset:4352
	v_cvt_pk_f16_f32 v21, v10, v11
	ds_read_b32 v10, v7 offset:21760
	v_cvt_pk_f16_f32 v33, v12, v13
	s_waitcnt lgkmcnt(1)
	v_cvt_f32_f16_e32 v9, v8
	v_cvt_f32_f16_sdwa v8, v8 dst_sel:DWORD dst_unused:UNUSED_PAD src0_sel:WORD_1
	s_waitcnt lgkmcnt(0)
	v_cvt_f32_f16_e32 v11, v10
	v_cvt_f32_f16_sdwa v10, v10 dst_sel:DWORD dst_unused:UNUSED_PAD src0_sel:WORD_1
	v_add_f32_e32 v12, v9, v11
	v_add_f32_e32 v13, v8, v10
	v_sub_f32_e32 v8, v8, v10
	v_sub_f32_e32 v9, v9, v11
	v_mul_f32_e32 v10, v12, v234
	v_mul_f32_e64 v11, -v12, v235
	v_fma_f32 v10, -v13, v235, v10
	v_fma_f32 v11, -v13, v234, v11
	v_mul_f32_e32 v12, v9, v236
	v_mul_f32_e64 v13, -v9, v237
	v_fma_f32 v12, -v8, v237, v12
	v_fma_f32 v13, -v8, v236, v13
	ds_read_b32 v8, v7 offset:6528
	ds_read_b32 v7, v7 offset:23936
	v_cvt_pk_f16_f32 v22, v10, v11
	v_cvt_pk_f16_f32 v34, v12, v13
	s_waitcnt lgkmcnt(1)
	v_cvt_f32_f16_e32 v9, v8
	v_cvt_f32_f16_sdwa v8, v8 dst_sel:DWORD dst_unused:UNUSED_PAD src0_sel:WORD_1
	s_waitcnt lgkmcnt(0)
	v_cvt_f32_f16_e32 v10, v7
	v_cvt_f32_f16_sdwa v7, v7 dst_sel:DWORD dst_unused:UNUSED_PAD src0_sel:WORD_1
	v_add_f32_e32 v11, v9, v10
	v_add_f32_e32 v12, v8, v7
	v_sub_f32_e32 v9, v9, v10
	v_sub_f32_e32 v7, v8, v7
	v_mul_f32_e32 v8, v11, v238
	v_mul_f32_e64 v10, -v11, v239
	v_fma_f32 v8, -v12, v239, v8
	v_fma_f32 v10, -v12, v238, v10
	v_mul_f32_e32 v11, v9, v240
	v_mul_f32_e64 v12, -v9, v241
	v_fma_f32 v11, -v7, v241, v11
	v_fma_f32 v12, -v7, v240, v12
	ds_read_b32 v7, v6
	ds_read_b32 v9, v6 offset:17408
	v_cvt_pk_f16_f32 v23, v8, v10
	v_cvt_pk_f16_f32 v35, v11, v12
	s_waitcnt lgkmcnt(1)
	v_cvt_f32_f16_e32 v8, v7
	v_cvt_f32_f16_sdwa v7, v7 dst_sel:DWORD dst_unused:UNUSED_PAD src0_sel:WORD_1
	s_waitcnt lgkmcnt(0)
	v_cvt_f32_f16_e32 v10, v9
	v_cvt_f32_f16_sdwa v9, v9 dst_sel:DWORD dst_unused:UNUSED_PAD src0_sel:WORD_1
	v_add_f32_e32 v11, v8, v10
	v_add_f32_e32 v12, v7, v9
	v_sub_f32_e32 v8, v8, v10
	v_sub_f32_e32 v7, v7, v9
	v_mul_f32_e32 v9, v11, v210
	v_mul_f32_e64 v10, -v11, v211
	v_fma_f32 v9, -v12, v211, v9
	v_fma_f32 v10, -v12, v210, v10
	v_mul_f32_e32 v11, v8, v212
	v_mul_f32_e64 v12, -v8, v213
	v_fma_f32 v11, -v7, v213, v11
	v_fma_f32 v12, -v7, v212, v12
	ds_read_b32 v7, v6 offset:2176
	v_cvt_pk_f16_f32 v36, v9, v10
	ds_read_b32 v9, v6 offset:19584
	v_cvt_pk_f16_f32 v48, v11, v12
	s_waitcnt lgkmcnt(1)
	v_cvt_f32_f16_e32 v8, v7
	v_cvt_f32_f16_sdwa v7, v7 dst_sel:DWORD dst_unused:UNUSED_PAD src0_sel:WORD_1
	s_waitcnt lgkmcnt(0)
	v_cvt_f32_f16_e32 v10, v9
	v_cvt_f32_f16_sdwa v9, v9 dst_sel:DWORD dst_unused:UNUSED_PAD src0_sel:WORD_1
	v_add_f32_e32 v11, v8, v10
	v_add_f32_e32 v12, v7, v9
	v_sub_f32_e32 v8, v8, v10
	v_sub_f32_e32 v7, v7, v9
	v_mul_f32_e32 v9, v11, v214
	v_mul_f32_e64 v10, -v11, v215
	v_fma_f32 v9, -v12, v215, v9
	v_fma_f32 v10, -v12, v214, v10
	v_mul_f32_e32 v11, v8, v216
	v_mul_f32_e64 v12, -v8, v217
	v_fma_f32 v11, -v7, v217, v11
	v_fma_f32 v12, -v7, v216, v12
	ds_read_b32 v7, v6 offset:4352
	v_cvt_pk_f16_f32 v37, v9, v10
	ds_read_b32 v9, v6 offset:21760
	v_cvt_pk_f16_f32 v49, v11, v12
	s_waitcnt lgkmcnt(1)
	v_cvt_f32_f16_e32 v8, v7
	v_cvt_f32_f16_sdwa v7, v7 dst_sel:DWORD dst_unused:UNUSED_PAD src0_sel:WORD_1
	s_waitcnt lgkmcnt(0)
	v_cvt_f32_f16_e32 v10, v9
	v_cvt_f32_f16_sdwa v9, v9 dst_sel:DWORD dst_unused:UNUSED_PAD src0_sel:WORD_1
	v_add_f32_e32 v11, v8, v10
	v_add_f32_e32 v12, v7, v9
	v_sub_f32_e32 v7, v7, v9
	v_sub_f32_e32 v8, v8, v10
	v_mul_f32_e32 v9, v11, v218
	v_mul_f32_e64 v10, -v11, v219
	v_fma_f32 v9, -v12, v219, v9
	v_fma_f32 v10, -v12, v218, v10
	v_mul_f32_e32 v11, v8, v220
	v_mul_f32_e64 v12, -v8, v221
	v_fma_f32 v11, -v7, v221, v11
	v_fma_f32 v12, -v7, v220, v12
	ds_read_b32 v7, v6 offset:6528
	ds_read_b32 v6, v6 offset:23936
	v_cvt_pk_f16_f32 v38, v9, v10
	v_cvt_pk_f16_f32 v50, v11, v12
	s_waitcnt lgkmcnt(1)
	v_cvt_f32_f16_e32 v8, v7
	v_cvt_f32_f16_sdwa v7, v7 dst_sel:DWORD dst_unused:UNUSED_PAD src0_sel:WORD_1
	s_waitcnt lgkmcnt(0)
	v_cvt_f32_f16_e32 v9, v6
	v_cvt_f32_f16_sdwa v6, v6 dst_sel:DWORD dst_unused:UNUSED_PAD src0_sel:WORD_1
	v_add_f32_e32 v10, v8, v9
	v_add_f32_e32 v11, v7, v6
	v_sub_f32_e32 v8, v8, v9
	v_sub_f32_e32 v6, v7, v6
	v_mul_f32_e32 v7, v10, v222
	v_mul_f32_e64 v9, -v10, v223
	v_fma_f32 v7, -v11, v223, v7
	v_fma_f32 v9, -v11, v222, v9
	v_mul_f32_e32 v10, v8, v224
	v_mul_f32_e64 v11, -v8, v225
	v_fma_f32 v10, -v6, v225, v10
	v_fma_f32 v11, -v6, v224, v11
	s_nop 0
	v_cvt_pk_f16_f32 v39, v7, v9
	ds_read_b32 v7, v4 offset:17408
	v_cvt_f32_f16_e32 v6, v5
	v_cvt_f32_f16_sdwa v5, v5 dst_sel:DWORD dst_unused:UNUSED_PAD src0_sel:WORD_1
	v_cvt_pk_f16_f32 v51, v10, v11
	s_waitcnt lgkmcnt(0)
	v_cvt_f32_f16_e32 v8, v7
	v_cvt_f32_f16_sdwa v7, v7 dst_sel:DWORD dst_unused:UNUSED_PAD src0_sel:WORD_1
	v_add_f32_e32 v9, v6, v8
	v_add_f32_e32 v10, v5, v7
	v_sub_f32_e32 v6, v6, v8
	v_sub_f32_e32 v5, v5, v7
	v_mul_f32_e32 v7, v9, v226
	v_mul_f32_e64 v8, -v9, v227
	v_fma_f32 v7, -v10, v227, v7
	v_fma_f32 v8, -v10, v226, v8
	v_mul_f32_e32 v9, v6, v228
	v_mul_f32_e64 v10, -v6, v229
	v_fma_f32 v9, -v5, v229, v9
	v_fma_f32 v10, -v5, v228, v10
	ds_read_b32 v5, v4 offset:2176
	v_cvt_pk_f16_f32 v52, v7, v8
	ds_read_b32 v7, v4 offset:19584
	v_cvt_pk_f16_f32 v128, v9, v10
	s_waitcnt lgkmcnt(1)
	v_cvt_f32_f16_e32 v6, v5
	v_cvt_f32_f16_sdwa v5, v5 dst_sel:DWORD dst_unused:UNUSED_PAD src0_sel:WORD_1
	s_waitcnt lgkmcnt(0)
	v_cvt_f32_f16_e32 v8, v7
	v_cvt_f32_f16_sdwa v7, v7 dst_sel:DWORD dst_unused:UNUSED_PAD src0_sel:WORD_1
	v_add_f32_e32 v9, v6, v8
	v_add_f32_e32 v10, v5, v7
	v_sub_f32_e32 v6, v6, v8
	v_sub_f32_e32 v5, v5, v7
	v_mul_f32_e32 v7, v9, v230
	v_mul_f32_e64 v8, -v9, v231
	v_fma_f32 v7, -v10, v231, v7
	v_fma_f32 v8, -v10, v230, v8
	v_mul_f32_e32 v9, v6, v232
	v_mul_f32_e64 v10, -v6, v233
	v_fma_f32 v9, -v5, v233, v9
	v_fma_f32 v10, -v5, v232, v10
	ds_read_b32 v5, v4 offset:4352
	v_cvt_pk_f16_f32 v53, v7, v8
	ds_read_b32 v7, v4 offset:21760
	v_cvt_pk_f16_f32 v129, v9, v10
	s_waitcnt lgkmcnt(1)
	v_cvt_f32_f16_e32 v6, v5
	v_cvt_f32_f16_sdwa v5, v5 dst_sel:DWORD dst_unused:UNUSED_PAD src0_sel:WORD_1
	s_waitcnt lgkmcnt(0)
	v_cvt_f32_f16_e32 v8, v7
	v_cvt_f32_f16_sdwa v7, v7 dst_sel:DWORD dst_unused:UNUSED_PAD src0_sel:WORD_1
	v_add_f32_e32 v9, v6, v8
	v_add_f32_e32 v10, v5, v7
	v_sub_f32_e32 v5, v5, v7
	v_sub_f32_e32 v6, v6, v8
	v_mul_f32_e32 v7, v9, v234
	v_mul_f32_e64 v8, -v9, v235
	v_fma_f32 v7, -v10, v235, v7
	v_fma_f32 v8, -v10, v234, v8
	v_mul_f32_e32 v9, v6, v236
	v_mul_f32_e64 v10, -v6, v237
	v_fma_f32 v9, -v5, v237, v9
	v_fma_f32 v10, -v5, v236, v10
	ds_read_b32 v5, v4 offset:6528
	ds_read_b32 v4, v4 offset:23936
	v_cvt_pk_f16_f32 v54, v7, v8
	v_cvt_pk_f16_f32 v130, v9, v10
	s_waitcnt lgkmcnt(1)
	v_cvt_f32_f16_e32 v6, v5
	v_cvt_f32_f16_sdwa v5, v5 dst_sel:DWORD dst_unused:UNUSED_PAD src0_sel:WORD_1
	s_waitcnt lgkmcnt(0)
	v_cvt_f32_f16_e32 v7, v4
	v_cvt_f32_f16_sdwa v4, v4 dst_sel:DWORD dst_unused:UNUSED_PAD src0_sel:WORD_1
	v_add_f32_e32 v8, v6, v7
	v_add_f32_e32 v9, v5, v4
	v_sub_f32_e32 v6, v6, v7
	v_sub_f32_e32 v4, v5, v4
	v_mul_f32_e32 v5, v8, v238
	v_mul_f32_e64 v7, -v8, v239
	v_fma_f32 v5, -v9, v239, v5
	v_fma_f32 v7, -v9, v238, v7
	v_mul_f32_e32 v8, v6, v240
	v_mul_f32_e64 v9, -v6, v241
	v_fma_f32 v8, -v4, v241, v8
	v_fma_f32 v9, -v4, v240, v9
	s_nop 0
	v_cvt_pk_f16_f32 v55, v5, v7
	v_cvt_pk_f16_f32 v131, v8, v9
	v_mfma_f32_32x32x16_f16 v[0:15], v[68:71], v[0:3], 0
	v_mfma_f32_32x32x16_f16 v[0:15], v[84:87], v[16:19], v[0:15]
	v_mfma_f32_32x32x16_f16 v[16:31], v[72:75], v[20:23], 0
	s_nop 10
	v_cvt_pk_f16_f32 v0, v0, v1
	v_add_u32_e32 v1, 0x8800, v251
	v_cvt_pk_f16_f32 v2, v2, v3
	ds_write2_b32 v1, v0, v2 offset1:1
	v_cvt_pk_f16_f32 v0, v4, v5
	v_add_u32_e32 v1, 0x8810, v251
	v_cvt_pk_f16_f32 v2, v6, v7
	v_mfma_f32_32x32x16_f16 v[16:31], v[88:91], v[32:35], v[16:31]
	ds_write2_b32 v1, v0, v2 offset1:1
	v_cvt_pk_f16_f32 v0, v8, v9
	v_add_u32_e32 v1, 0x8820, v251
	v_cvt_pk_f16_f32 v2, v10, v11
	ds_write2_b32 v1, v0, v2 offset1:1
	v_cvt_pk_f16_f32 v0, v12, v13
	v_add_u32_e32 v1, 0x8830, v251
	v_mfma_f32_32x32x16_f16 v[32:47], v[68:71], v[36:39], 0
	v_cvt_pk_f16_f32 v2, v14, v15
	ds_write2_b32 v1, v0, v2 offset1:1
	s_nop 1
	v_cvt_pk_f16_f32 v0, v16, v17
	v_add_u32_e32 v1, 0x8800, v250
	v_cvt_pk_f16_f32 v2, v18, v19
	ds_write2_b32 v1, v0, v2 offset1:1
	v_cvt_pk_f16_f32 v0, v20, v21
	v_mfma_f32_32x32x16_f16 v[32:47], v[84:87], v[48:51], v[32:47]
	v_add_u32_e32 v1, 0x8810, v250
	v_cvt_pk_f16_f32 v2, v22, v23
	ds_write2_b32 v1, v0, v2 offset1:1
	v_cvt_pk_f16_f32 v0, v24, v25
	v_add_u32_e32 v1, 0x8820, v250
	v_cvt_pk_f16_f32 v2, v26, v27
	ds_write2_b32 v1, v0, v2 offset1:1
	v_mfma_f32_32x32x16_f16 v[48:63], v[72:75], v[52:55], 0
	v_cvt_pk_f16_f32 v0, v28, v29
	v_add_u32_e32 v1, 0x8830, v250
	v_cvt_pk_f16_f32 v2, v30, v31
	ds_write2_b32 v1, v0, v2 offset1:1
	v_add_u32_e32 v0, 0x19800, v247
	v_add_u32_e32 v1, v0, v248
	v_cvt_pk_f16_f32 v2, v32, v33
	v_mfma_f32_32x32x16_f16 v[48:63], v[88:91], v[128:131], v[48:63]
	v_cvt_pk_f16_f32 v3, v34, v35
	ds_write2_b32 v1, v2, v3 offset1:1
	v_cvt_pk_f16_f32 v2, v36, v37
	v_cvt_pk_f16_f32 v3, v38, v39
	ds_write2_b32 v1, v2, v3 offset0:4 offset1:5
	v_cvt_pk_f16_f32 v2, v40, v41
	v_cvt_pk_f16_f32 v3, v42, v43
	ds_write2_b32 v1, v2, v3 offset0:8 offset1:9
	v_cvt_pk_f16_f32 v2, v44, v45
	v_cvt_pk_f16_f32 v3, v46, v47
	ds_write2_b32 v1, v2, v3 offset0:12 offset1:13
	v_add_u32_e32 v0, v0, v249
	v_cvt_pk_f16_f32 v1, v48, v49
	v_cvt_pk_f16_f32 v2, v50, v51
	ds_write2_b32 v0, v1, v2 offset1:1
	v_cvt_pk_f16_f32 v1, v52, v53
	v_cvt_pk_f16_f32 v2, v54, v55
	ds_write2_b32 v0, v1, v2 offset0:4 offset1:5
	v_cvt_pk_f16_f32 v1, v56, v57
	v_cvt_pk_f16_f32 v2, v58, v59
	ds_write2_b32 v0, v1, v2 offset0:8 offset1:9
	v_cvt_pk_f16_f32 v1, v60, v61
	v_cvt_pk_f16_f32 v2, v62, v63
	v_mov_b32_e32 v248, v209
	ds_write2_b32 v0, v1, v2 offset0:12 offset1:13
	s_waitcnt lgkmcnt(0)
	s_barrier
	s_nop 0
	v_and_b32_e32 v0, 0xffffffdf, v248
	v_bfe_u32 v247, v248, 5, 1
	v_ashrrev_i32_e32 v249, 4, v0
	v_mad_u32_u24 v12, v247, s84, 0
	v_add_lshl_u32 v13, v249, v0, 2
	v_add_u32_e32 v7, v12, v13
	ds_read_b32 v0, v7 offset:34816
	ds_read_b32 v4, v7 offset:52224
	ds_read_b32 v1, v7 offset:36992
	ds_read_b32 v5, v7 offset:54400
	ds_read_b32 v2, v7 offset:39168
	ds_read_b32 v6, v7 offset:56576
	ds_read_b32 v3, v7 offset:41344
	ds_read_b32 v7, v7 offset:58752
	v_or_b32_e32 v8, 32, v248
	s_waitcnt lgkmcnt(1)
	v_mfma_f32_32x32x16_f16 v[48:63], v[64:67], v[0:3], 0
	v_ashrrev_i32_e32 v250, 4, v8
	v_add_lshl_u32 v14, v250, v8, 2
	v_add_u32_e32 v15, v12, v14
	ds_read_b32 v8, v15 offset:34816
	ds_read_b32 v20, v15 offset:52224
	ds_read_b32 v9, v15 offset:36992
	ds_read_b32 v21, v15 offset:54400
	ds_read_b32 v10, v15 offset:39168
	ds_read_b32 v22, v15 offset:56576
	ds_read_b32 v11, v15 offset:41344
	ds_read_b32 v23, v15 offset:58752
	v_add_u32_e32 v12, 0x19800, v12
	v_add_u32_e32 v13, v12, v13
	v_add_u32_e32 v12, v12, v14
	ds_read_b32 v16, v13
	ds_read_b32 v36, v13 offset:17408
	ds_read_b32 v17, v13 offset:2176
	ds_read_b32 v37, v13 offset:19584
	ds_read_b32 v18, v13 offset:4352
	ds_read_b32 v38, v13 offset:21760
	ds_read_b32 v19, v13 offset:6528
	ds_read_b32 v39, v13 offset:23936
	ds_read_b32 v32, v12
	ds_read_b32 v128, v12 offset:17408
	ds_read_b32 v33, v12 offset:2176
	ds_read_b32 v129, v12 offset:19584
	ds_read_b32 v34, v12 offset:4352
	ds_read_b32 v130, v12 offset:21760
	ds_read_b32 v35, v12 offset:6528
	ds_read_b32 v131, v12 offset:23936
	s_waitcnt lgkmcnt(14)
	v_mfma_f32_32x32x16_f16 v[48:63], v[80:83], v[4:7], v[48:63]
	s_nop 15
	s_nop 3
	v_mfma_f32_32x32x16_f16 v[0:15], v[64:67], v[8:11], 0
	v_mfma_f32_32x32x16_f16 v[0:15], v[80:83], v[20:23], v[0:15]
	s_waitcnt lgkmcnt(9)
	v_mfma_f32_32x32x16_f16 v[16:31], v[64:67], v[16:19], 0
	s_waitcnt lgkmcnt(8)
	v_mfma_f32_32x32x16_f16 v[16:31], v[80:83], v[36:39], v[16:31]
	s_waitcnt lgkmcnt(1)
	v_mfma_f32_32x32x16_f16 v[32:47], v[64:67], v[32:35], 0
	s_waitcnt lgkmcnt(0)
	v_mfma_f32_32x32x16_f16 v[32:47], v[80:83], v[128:131], v[32:47]
	v_and_b32_e32 v128, 15, v248
	v_mul_lo_u32 v130, v249, s86
	v_or_b32_e32 v130, v130, v128
	v_mul_f32_e32 v249, v48, v173
	v_mul_f32_e32 v251, v48, v174
	v_fma_f32 v249, -v49, v174, v249
	v_fma_f32 v251, v49, v173, v251
	v_mad_u32_u24 v129, v247, s89, 0
	v_lshlrev_b32_e32 v130, 2, v130
	v_cvt_pk_f16_f32 v48, v249, v251
	v_mul_f32_e32 v49, v50, v175
	v_mul_f32_e32 v249, v50, v176
	v_fma_f32 v49, -v51, v176, v49
	v_fma_f32 v249, v51, v175, v249
	v_add_u32_e32 v131, v129, v130
	v_cvt_pk_f16_f32 v49, v49, v249
	ds_write2_b32 v131, v48, v49 offset1:17
	v_mul_f32_e32 v48, v52, v177
	v_mul_f32_e32 v49, v52, v178
	v_fma_f32 v48, -v53, v178, v48
	v_fma_f32 v49, v53, v177, v49
	v_ashrrev_i32_e32 v249, 8, v248
	v_cvt_pk_f16_f32 v48, v48, v49
	v_mul_f32_e32 v49, v54, v179
	v_mul_f32_e32 v50, v54, v180
	v_fma_f32 v49, -v55, v180, v49
	v_fma_f32 v50, v55, v179, v50
	s_nop 0
	v_cvt_pk_f16_f32 v49, v49, v50
	ds_write2_b32 v131, v48, v49 offset0:68 offset1:85
	v_mul_f32_e32 v48, v56, v181
	v_mul_f32_e32 v49, v56, v182
	v_fma_f32 v48, -v57, v182, v48
	v_fma_f32 v49, v57, v181, v49
	s_nop 0
	v_cvt_pk_f16_f32 v48, v48, v49
	v_mul_f32_e32 v49, v58, v183
	v_mul_f32_e32 v50, v58, v184
	v_fma_f32 v49, -v59, v184, v49
	v_fma_f32 v50, v59, v183, v50
	s_nop 0
	v_cvt_pk_f16_f32 v49, v49, v50
	ds_write2_b32 v131, v48, v49 offset0:136 offset1:153
	v_mul_f32_e32 v48, v60, v185
	v_mul_f32_e32 v49, v60, v186
	v_fma_f32 v48, -v61, v186, v48
	v_fma_f32 v49, v61, v185, v49
	s_nop 0
	v_cvt_pk_f16_f32 v48, v48, v49
	v_mul_f32_e32 v49, v62, v187
	v_mul_f32_e32 v50, v62, v188
	v_fma_f32 v49, -v63, v188, v49
	v_fma_f32 v50, v63, v187, v50
	s_nop 0
	v_cvt_pk_f16_f32 v49, v49, v50
	ds_write2_b32 v131, v48, v49 offset0:204 offset1:221
	v_mul_lo_u32 v48, v250, s86
	v_or_b32_e32 v48, v48, v128
	s_nop 15
	s_nop 3
	v_lshlrev_b32_e32 v48, 2, v48
	v_mul_f32_e32 v50, v0, v189
	v_mul_f32_e32 v51, v0, v190
	v_fma_f32 v50, -v1, v190, v50
	v_fma_f32 v51, v1, v189, v51
	v_add_u32_e32 v49, v129, v48
	v_cvt_pk_f16_f32 v0, v50, v51
	v_mul_f32_e32 v1, v2, v191
	v_mul_f32_e32 v50, v2, v192
	v_fma_f32 v1, -v3, v192, v1
	v_fma_f32 v50, v3, v191, v50
	s_nop 0
	v_cvt_pk_f16_f32 v1, v1, v50
	ds_write2_b32 v49, v0, v1 offset1:17
	v_mul_f32_e32 v0, v4, v193
	v_mul_f32_e32 v1, v4, v194
	v_fma_f32 v0, -v5, v194, v0
	v_fma_f32 v1, v5, v193, v1
	s_nop 0
	v_cvt_pk_f16_f32 v0, v0, v1
	v_mul_f32_e32 v1, v6, v195
	v_mul_f32_e32 v2, v6, v196
	v_fma_f32 v1, -v7, v196, v1
	v_fma_f32 v2, v7, v195, v2
	s_nop 0
	v_cvt_pk_f16_f32 v1, v1, v2
	ds_write2_b32 v49, v0, v1 offset0:68 offset1:85
	v_mul_f32_e32 v0, v8, v197
	v_mul_f32_e32 v1, v8, v198
	v_fma_f32 v0, -v9, v198, v0
	v_fma_f32 v1, v9, v197, v1
	s_nop 0
	v_cvt_pk_f16_f32 v0, v0, v1
	v_mul_f32_e32 v1, v10, v199
	v_mul_f32_e32 v2, v10, v200
	v_fma_f32 v1, -v11, v200, v1
	v_fma_f32 v2, v11, v199, v2
	s_nop 0
	v_cvt_pk_f16_f32 v1, v1, v2
	ds_write2_b32 v49, v0, v1 offset0:136 offset1:153
	v_mul_f32_e32 v0, v12, v201
	v_mul_f32_e32 v1, v12, v202
	v_fma_f32 v0, -v13, v202, v0
	v_fma_f32 v1, v13, v201, v1
	s_nop 0
	v_cvt_pk_f16_f32 v0, v0, v1
	v_mul_f32_e32 v1, v14, v203
	v_mul_f32_e32 v2, v14, v204
	v_fma_f32 v1, -v15, v204, v1
	v_fma_f32 v2, v15, v203, v2
	s_nop 0
	v_cvt_pk_f16_f32 v1, v1, v2
	ds_write2_b32 v49, v0, v1 offset0:204 offset1:221
	s_nop 15
	s_nop 3
	v_add_u32_e32 v0, 0x11000, v129
	v_mul_f32_e32 v2, v16, v173
	v_mul_f32_e32 v3, v16, v174
	v_fma_f32 v2, -v17, v174, v2
	v_fma_f32 v3, v17, v173, v3
	v_add_u32_e32 v1, v0, v130
	v_cvt_pk_f16_f32 v2, v2, v3
	v_mul_f32_e32 v3, v18, v175
	v_mul_f32_e32 v4, v18, v176
	v_fma_f32 v3, -v19, v176, v3
	v_fma_f32 v4, v19, v175, v4
	v_add_u32_e32 v0, v0, v48
	v_cvt_pk_f16_f32 v3, v3, v4
	ds_write2_b32 v1, v2, v3 offset1:17
	v_mul_f32_e32 v2, v20, v177
	v_mul_f32_e32 v3, v20, v178
	v_fma_f32 v2, -v21, v178, v2
	v_fma_f32 v3, v21, v177, v3
	s_nop 0
	v_cvt_pk_f16_f32 v2, v2, v3
	v_mul_f32_e32 v3, v22, v179
	v_mul_f32_e32 v4, v22, v180
	v_fma_f32 v3, -v23, v180, v3
	v_fma_f32 v4, v23, v179, v4
	s_nop 0
	v_cvt_pk_f16_f32 v3, v3, v4
	ds_write2_b32 v1, v2, v3 offset0:68 offset1:85
	v_mul_f32_e32 v2, v24, v181
	v_mul_f32_e32 v3, v24, v182
	v_fma_f32 v2, -v25, v182, v2
	v_fma_f32 v3, v25, v181, v3
	s_nop 0
	v_cvt_pk_f16_f32 v2, v2, v3
	v_mul_f32_e32 v3, v26, v183
	v_mul_f32_e32 v4, v26, v184
	v_fma_f32 v3, -v27, v184, v3
	v_fma_f32 v4, v27, v183, v4
	s_nop 0
	v_cvt_pk_f16_f32 v3, v3, v4
	ds_write2_b32 v1, v2, v3 offset0:136 offset1:153
	v_mul_f32_e32 v2, v28, v185
	v_mul_f32_e32 v3, v28, v186
	v_fma_f32 v2, -v29, v186, v2
	v_fma_f32 v3, v29, v185, v3
	s_nop 0
	v_cvt_pk_f16_f32 v2, v2, v3
	v_mul_f32_e32 v3, v30, v187
	v_mul_f32_e32 v4, v30, v188
	v_fma_f32 v3, -v31, v188, v3
	v_fma_f32 v4, v31, v187, v4
	s_nop 0
	v_cvt_pk_f16_f32 v3, v3, v4
	ds_write2_b32 v1, v2, v3 offset0:204 offset1:221
	s_nop 15
	s_nop 3
	v_and_b32_e32 v4, 0xdf, v248
	v_mul_f32_e32 v1, v32, v189
	v_mul_f32_e32 v2, v32, v190
	v_fma_f32 v1, -v33, v190, v1
	v_fma_f32 v2, v33, v189, v2
	v_mad_i32_i24 v248, v249, s87, 0
	v_cvt_pk_f16_f32 v1, v1, v2
	v_mul_f32_e32 v2, v34, v191
	v_mul_f32_e32 v3, v34, v192
	v_fma_f32 v2, -v35, v192, v2
	v_fma_f32 v3, v35, v191, v3
	v_mad_u32_u24 v5, v247, s84, v248
	v_cvt_pk_f16_f32 v2, v2, v3
	ds_write2_b32 v0, v1, v2 offset1:17
	v_mul_f32_e32 v1, v36, v193
	v_mul_f32_e32 v2, v36, v194
	v_fma_f32 v1, -v37, v194, v1
	v_fma_f32 v2, v37, v193, v2
	s_nop 0
	v_cvt_pk_f16_f32 v1, v1, v2
	v_mul_f32_e32 v2, v38, v195
	v_mul_f32_e32 v3, v38, v196
	v_fma_f32 v2, -v39, v196, v2
	v_fma_f32 v3, v39, v195, v3
	s_nop 0
	v_cvt_pk_f16_f32 v2, v2, v3
	ds_write2_b32 v0, v1, v2 offset0:68 offset1:85
	v_mul_f32_e32 v1, v40, v197
	v_mul_f32_e32 v2, v40, v198
	v_fma_f32 v1, -v41, v198, v1
	v_fma_f32 v2, v41, v197, v2
	s_nop 0
	v_cvt_pk_f16_f32 v1, v1, v2
	v_mul_f32_e32 v2, v42, v199
	v_mul_f32_e32 v3, v42, v200
	v_fma_f32 v2, -v43, v200, v2
	v_fma_f32 v3, v43, v199, v3
	s_nop 0
	v_cvt_pk_f16_f32 v2, v2, v3
	ds_write2_b32 v0, v1, v2 offset0:136 offset1:153
	v_mul_f32_e32 v1, v44, v201
	v_mul_f32_e32 v2, v44, v202
	v_fma_f32 v1, -v45, v202, v1
	v_fma_f32 v2, v45, v201, v2
	s_nop 0
	v_cvt_pk_f16_f32 v1, v1, v2
	v_mul_f32_e32 v2, v46, v203
	v_mul_f32_e32 v3, v46, v204
	v_fma_f32 v2, -v47, v204, v2
	v_fma_f32 v3, v47, v203, v3
	s_nop 0
	v_cvt_pk_f16_f32 v2, v2, v3
	ds_write2_b32 v0, v1, v2 offset0:204 offset1:221
	v_lshrrev_b32_e32 v0, 4, v4
	v_add_lshl_u32 v250, v0, v4, 2
	v_add_u32_e32 v6, v5, v250
	v_or_b32_e32 v4, 32, v4
	s_waitcnt lgkmcnt(0)
	s_barrier
	ds_read_b32 v0, v6
	ds_read_b32 v16, v6 offset:17408
	ds_read_b32 v1, v6 offset:2176
	ds_read_b32 v17, v6 offset:19584
	ds_read_b32 v2, v6 offset:4352
	ds_read_b32 v18, v6 offset:21760
	ds_read_b32 v3, v6 offset:6528
	ds_read_b32 v19, v6 offset:23936
	v_lshrrev_b32_e32 v6, 4, v4
	v_add_lshl_u32 v251, v6, v4, 2
	v_add_u32_e32 v4, v5, v251
	ds_read_b32 v20, v4
	ds_read_b32 v36, v4 offset:17408
	ds_read_b32 v21, v4 offset:2176
	ds_read_b32 v37, v4 offset:19584
	ds_read_b32 v22, v4 offset:4352
	ds_read_b32 v38, v4 offset:21760
	ds_read_b32 v23, v4 offset:6528
	ds_read_b32 v39, v4 offset:23936
	v_add_u32_e32 v4, 0x11000, v5
	v_add_u32_e32 v5, v4, v250
	v_add_u32_e32 v4, v4, v251
	ds_read_b32 v32, v5
	ds_read_b32 v52, v5 offset:17408
	ds_read_b32 v33, v5 offset:2176
	ds_read_b32 v53, v5 offset:19584
	ds_read_b32 v34, v5 offset:4352
	ds_read_b32 v54, v5 offset:21760
	ds_read_b32 v35, v5 offset:6528
	ds_read_b32 v55, v5 offset:23936
	ds_read_b32 v48, v4
	ds_read_b32 v128, v4 offset:17408
	ds_read_b32 v49, v4 offset:2176
	ds_read_b32 v129, v4 offset:19584
	ds_read_b32 v50, v4 offset:4352
	ds_read_b32 v130, v4 offset:21760
	ds_read_b32 v51, v4 offset:6528
	ds_read_b32 v131, v4 offset:23936
	s_waitcnt lgkmcnt(14)
	v_mfma_f32_32x32x16_f16 v[0:15], v[76:79], v[0:3], 0
	v_mfma_f32_32x32x16_f16 v[0:15], v[92:95], v[16:19], v[0:15]
	v_mfma_f32_32x32x16_f16 v[16:31], v[76:79], v[20:23], 0
	s_nop 10
	v_cvt_pk_f16_f32 v0, v0, v1
	v_mfma_f32_32x32x16_f16 v[16:31], v[92:95], v[36:39], v[16:31]
	s_waitcnt lgkmcnt(9)
	v_mfma_f32_32x32x16_f16 v[32:47], v[76:79], v[32:35], 0
	s_nop 9
	v_cvt_pk_f16_f32 v1, v16, v17
	s_waitcnt lgkmcnt(8)
	v_mfma_f32_32x32x16_f16 v[32:47], v[92:95], v[52:55], v[32:47]
	s_waitcnt lgkmcnt(1)
	v_mfma_f32_32x32x16_f16 v[48:63], v[76:79], v[48:51], 0
	s_waitcnt lgkmcnt(0)
	v_mfma_f32_32x32x16_f16 v[48:63], v[92:95], v[128:131], v[48:63]
	v_mul_i32_i24_e32 v128, 0x3fc0, v249
	v_mul_u32_u24_e32 v129, 0x880, v247
	v_add3_u32 v128, v248, v128, v129
	v_add_u32_e32 v129, v128, v250
	ds_write_b32 v129, v0 offset:34816
	v_cvt_pk_f16_f32 v0, v2, v3
	ds_write_b32 v129, v0 offset:35904
	v_cvt_pk_f16_f32 v0, v4, v5
	ds_write_b32 v129, v0 offset:39168
	v_cvt_pk_f16_f32 v0, v6, v7
	ds_write_b32 v129, v0 offset:40256
	v_cvt_pk_f16_f32 v0, v8, v9
	ds_write_b32 v129, v0 offset:43520
	v_cvt_pk_f16_f32 v0, v10, v11
	ds_write_b32 v129, v0 offset:44608
	v_cvt_pk_f16_f32 v0, v12, v13
	ds_write_b32 v129, v0 offset:47872
	v_cvt_pk_f16_f32 v0, v14, v15
	ds_write_b32 v129, v0 offset:48960
	v_add_u32_e32 v0, v128, v251
	ds_write_b32 v0, v1 offset:34816
	v_cvt_pk_f16_f32 v1, v18, v19
	ds_write_b32 v0, v1 offset:35904
	v_cvt_pk_f16_f32 v1, v20, v21
	ds_write_b32 v0, v1 offset:39168
	v_cvt_pk_f16_f32 v1, v22, v23
	ds_write_b32 v0, v1 offset:40256
	v_cvt_pk_f16_f32 v1, v24, v25
	ds_write_b32 v0, v1 offset:43520
	v_cvt_pk_f16_f32 v1, v26, v27
	ds_write_b32 v0, v1 offset:44608
	v_cvt_pk_f16_f32 v1, v28, v29
	ds_write_b32 v0, v1 offset:47872
	v_cvt_pk_f16_f32 v1, v30, v31
	ds_write_b32 v0, v1 offset:48960
	v_add_u32_e32 v0, 0x19800, v128
	v_add_u32_e32 v1, v0, v250
	v_cvt_pk_f16_f32 v2, v32, v33
	ds_write_b32 v1, v2
	v_cvt_pk_f16_f32 v2, v34, v35
	ds_write_b32 v1, v2 offset:1088
	v_cvt_pk_f16_f32 v2, v36, v37
	ds_write_b32 v1, v2 offset:4352
	v_cvt_pk_f16_f32 v2, v38, v39
	ds_write_b32 v1, v2 offset:5440
	v_cvt_pk_f16_f32 v2, v40, v41
	ds_write_b32 v1, v2 offset:8704
	v_cvt_pk_f16_f32 v2, v42, v43
	ds_write_b32 v1, v2 offset:9792
	v_cvt_pk_f16_f32 v2, v44, v45
	ds_write_b32 v1, v2 offset:13056
	v_cvt_pk_f16_f32 v2, v46, v47
	ds_write_b32 v1, v2 offset:14144
	v_add_u32_e32 v0, v0, v251
	v_cvt_pk_f16_f32 v1, v48, v49
	ds_write_b32 v0, v1
	v_cvt_pk_f16_f32 v1, v50, v51
	ds_write_b32 v0, v1 offset:1088
	v_cvt_pk_f16_f32 v1, v52, v53
	ds_write_b32 v0, v1 offset:4352
	v_cvt_pk_f16_f32 v1, v54, v55
	ds_write_b32 v0, v1 offset:5440
	v_cvt_pk_f16_f32 v1, v56, v57
	ds_write_b32 v0, v1 offset:8704
	v_cvt_pk_f16_f32 v1, v58, v59
	ds_write_b32 v0, v1 offset:9792
	v_cvt_pk_f16_f32 v1, v60, v61
	ds_write_b32 v0, v1 offset:13056
	v_cvt_pk_f16_f32 v1, v62, v63
	ds_write_b32 v0, v1 offset:14144
	v_lshl_add_u64 v[0:1], v[160:161], 0, s[92:93]
	s_waitcnt lgkmcnt(0)
	s_barrier
	global_load_dwordx4 v[12:15], v[0:1], off nt
	global_load_ushort v24, v[0:1], off offset:-2 nt
	global_load_ushort v25, v[0:1], off offset:16 nt
	v_mov_b32_e32 v0, 0
	v_mov_b32_e32 v8, 0
	v_mov_b32_e32 v9, 0
	v_mov_b32_e32 v10, 0
	v_mov_b32_e32 v11, 0
	s_cbranch_vccnz .LBB0_1802
	s_add_i32 s92, s8, s51
	s_ashr_i32 s93, s92, 31
	s_lshl_b64 s[92:93], s[92:93], 13
	v_lshl_add_u64 v[2:3], v[160:161], 0, s[92:93]
	global_load_dwordx4 v[8:11], v[2:3], off nt
.LBB0_1802:
	s_add_i32 s92, s91, s9
	s_ashr_i32 s93, s92, 31
	s_lshl_b64 s[92:93], s[92:93], 13
	v_lshl_add_u64 v[2:3], v[160:161], 0, s[92:93]
	global_load_dwordx4 v[4:7], v[2:3], off nt
	global_load_ushort v29, v[2:3], off offset:16 nt
	global_load_ushort v28, v[2:3], off offset:-2 nt
	s_and_b64 vcc, exec, s[6:7]
	v_mov_b32_e32 v1, 0
	v_mov_b32_e32 v2, 0
	v_mov_b32_e32 v3, 0
	s_cbranch_vccnz .LBB0_1804
	s_add_i32 s6, s9, s51
	s_ashr_i32 s7, s6, 31
	s_lshl_b64 s[6:7], s[6:7], 13
	v_lshl_add_u64 v[0:1], v[160:161], 0, s[6:7]
	global_load_dwordx4 v[0:3], v[0:1], off nt

.LBB0_1811:
	s_waitcnt vmcnt(3)
	s_nop 0
	v_lshlrev_b32_e32 v16, 16, v25
	v_cndmask_b32_e64 v52, 0, v16, s[4:5]
	global_load_dwordx4 v[108:111], v[164:165], off nt
	global_load_dwordx4 v[100:103], v[164:165], off offset:16 nt
	global_load_dwordx4 v[16:19], v[166:167], off nt
	global_load_dwordx4 v[20:23], v[166:167], off offset:16 nt
	v_add_u32_e32 v26, 0x8800, v26
	v_add_u32_e32 v25, 0x11000, v26
	ds_read_b128 v[36:39], v25
	v_add_u32_e32 v25, 0x15400, v26
	ds_read_b128 v[40:43], v25
	v_add_u32_e32 v25, 0x11010, v26
	ds_read_b128 v[44:47], v25
	v_add_u32_e32 v25, 0x15410, v26
	ds_read_b128 v[48:51], v25
	s_waitcnt lgkmcnt(2)
	v_pk_add_f16 v35, v36, v40
	v_pk_add_f16 v37, v37, v41
	v_cvt_f32_f16_e32 v54, v35
	v_cvt_f32_f16_e32 v55, v37
	v_cvt_f32_f16_e32 v57, v105
	v_cvt_f32_f16_e32 v56, v104
	v_lshlrev_b32_e32 v26, 16, v12
	v_lshlrev_b32_e32 v24, 16, v24
	v_and_b32_e32 v12, 0xffff0000, v12
	s_waitcnt lgkmcnt(0)
	v_pk_add_f16 v32, v44, v48
	v_pk_add_f16 v34, v45, v49
	v_cndmask_b32_e64 v24, 0, v24, s[0:1]
	v_and_b32_e32 v49, 16, v14
	v_and_b32_e32 v48, 0xffff0000, v13
	v_lshlrev_b32_e32 v13, 16, v13
	v_mov_b32_e32 v25, v12
	v_pk_add_f16 v33, v38, v42
	v_pk_add_f16 v36, v39, v43
	v_and_b32_e32 v38, 0xffff0000, v15
	v_lshlrev_b32_e32 v43, 16, v15
	v_and_b32_e32 v45, 16, v15
	v_and_b32_e32 v44, 0xffff0000, v14
	v_lshlrev_b32_e32 v15, 16, v14
	v_mov_b32_e32 v14, v48
	v_pk_mul_f32 v[24:25], v[170:171], v[24:25]
	v_pk_mov_b32 v[48:49], v[12:13], v[48:49] op_sel:[1,0]
	v_pk_add_f16 v30, v46, v50
	v_pk_add_f16 v31, v47, v51
	v_cvt_f32_f16_e32 v51, v36
	v_cvt_f32_f16_e32 v50, v33
	v_pk_fma_f32 v[54:55], v[154:155], v[56:57], v[54:55]
	v_pk_fma_f32 v[24:25], v[168:169], v[26:27], v[24:25] op_sel_hi:[1,0,1]
	v_cvt_f32_f16_e32 v57, v107
	v_cvt_f32_f16_e32 v56, v106
	v_pk_mul_f32 v[48:49], v[156:157], v[48:49]
	v_mov_b32_e32 v42, v44
	v_cvt_f32_f16_e32 v47, v34
	v_cvt_f32_f16_e32 v46, v32
	v_pk_fma_f32 v[24:25], v[158:159], v[12:13], v[24:25]
	v_pk_fma_f32 v[12:13], v[150:151], v[12:13], v[48:49]
	v_cvt_f32_f16_e32 v49, v97
	v_cvt_f32_f16_e32 v48, v96
	v_pk_mov_b32 v[44:45], v[14:15], v[44:45] op_sel:[1,0]
	v_pk_add_f32 v[24:25], v[152:153], v[24:25]
	v_pk_mul_f32 v[44:45], v[156:157], v[44:45]
	v_pk_fma_f32 v[12:13], v[158:159], v[14:15], v[12:13]
	v_pk_fma_f32 v[14:15], v[150:151], v[14:15], v[44:45]
	v_pk_mul_f32 v[26:27], v[24:25], v[54:55]
	v_pk_fma_f32 v[24:25], v[154:155], v[56:57], v[50:51]
	v_pk_add_f32 v[12:13], v[152:153], v[12:13]
	v_pk_fma_f32 v[14:15], v[158:159], v[42:43], v[14:15]
	v_pk_mul_f32 v[12:13], v[12:13], v[24:25]
	v_pk_fma_f32 v[24:25], v[154:155], v[48:49], v[46:47]
	v_pk_add_f32 v[14:15], v[152:153], v[14:15]
	v_cvt_f32_f16_e32 v41, v30
	v_cvt_f32_f16_e32 v40, v31
	v_mov_b32_e32 v39, v43
	v_pk_mul_f32 v[14:15], v[14:15], v[24:25]
	v_pk_mul_f32 v[24:25], v[150:151], v[42:43]
	v_cvt_f32_f16_e32 v43, v98
	v_cvt_f32_f16_e32 v42, v99
	s_lshl_b32 s10, s60, 1
	v_mov_b32_e32 v53, v38
	v_pk_fma_f32 v[24:25], v[156:157], v[38:39], v[24:25] op_sel:[0,0,1] op_sel_hi:[1,1,0]
	s_or_b32 s10, s10, 1
	v_pk_fma_f32 v[24:25], v[158:159], v[52:53], v[24:25]
	s_lshl_b32 s60, s10, 11
	v_pk_add_f32 v[24:25], v[152:153], v[24:25]
	v_pk_fma_f32 v[38:39], v[154:155], v[42:43], v[40:41]
	s_add_i32 s60, s60, s44
	s_and_b64 vcc, exec, s[6:7]
	v_pk_mul_f32 v[24:25], v[24:25], v[38:39]
	s_cbranch_vccnz .LBB0_1813
	v_lshlrev_b32_e32 v38, 16, v8
	v_and_b32_e32 v39, 0xffff0000, v8
	v_mul_f32_e32 v8, 0xbfb8aa3b, v38
	v_exp_f32_e32 v8, v8
	v_mul_f32_e32 v40, 0xbfb8aa3b, v39
	v_exp_f32_e32 v41, v40
	s_ashr_i32 s61, s60, 31
	v_add_f32_e32 v8, 1.0, v8
	v_rcp_f32_e32 v40, v8
	v_add_f32_e32 v8, 1.0, v41
	v_rcp_f32_e32 v41, v8
	v_lshlrev_b32_e32 v8, 16, v9
	v_and_b32_e32 v9, 0xffff0000, v9
	s_lshl_b64 s[92:93], s[60:61], 13
	v_pk_mul_f32 v[38:39], v[40:41], v[38:39]
	v_mul_f32_e32 v40, 0xbfb8aa3b, v8
	v_mul_f32_e32 v41, 0xbfb8aa3b, v9
	v_exp_f32_e32 v40, v40
	v_exp_f32_e32 v41, v41
	v_pk_mul_f32 v[26:27], v[38:39], v[26:27]
	v_add_f32_e32 v38, 1.0, v40
	v_add_f32_e32 v39, 1.0, v41
	v_rcp_f32_e32 v38, v38
	v_rcp_f32_e32 v39, v39
	v_lshlrev_b32_e32 v40, 16, v10
	v_and_b32_e32 v41, 0xffff0000, v10
	v_mul_f32_e32 v10, 0xbfb8aa3b, v40
	v_pk_mul_f32 v[8:9], v[38:39], v[8:9]
	v_lshlrev_b32_e32 v38, 16, v11
	v_mul_f32_e32 v42, 0xbfb8aa3b, v41
	v_and_b32_e32 v39, 0xffff0000, v11
	v_mul_f32_e32 v11, 0xbfb8aa3b, v38
	v_exp_f32_e32 v10, v10
	v_exp_f32_e32 v42, v42
	v_exp_f32_e32 v43, v11
	v_mul_f32_e32 v11, 0xbfb8aa3b, v39
	v_exp_f32_e32 v44, v11
	v_add_f32_e32 v10, 1.0, v10
	v_add_f32_e32 v42, 1.0, v42
	v_rcp_f32_e32 v10, v10
	v_rcp_f32_e32 v11, v42
	v_add_f32_e32 v42, 1.0, v43
	v_add_f32_e32 v43, 1.0, v44
	v_rcp_f32_e32 v42, v42
	v_rcp_f32_e32 v43, v43
	v_pk_mul_f32 v[12:13], v[8:9], v[12:13]
	v_pk_mul_f32 v[8:9], v[10:11], v[40:41]
	s_nop 0
	v_pk_mul_f32 v[10:11], v[8:9], v[14:15]
	v_pk_mul_f32 v[8:9], v[42:43], v[38:39]
	v_cvt_pk_bf16_f32 v10, v10, v11
	v_pk_mul_f32 v[14:15], v[8:9], v[24:25] op_sel:[0,1] op_sel_hi:[1,0]
	v_cvt_pk_bf16_f32 v8, v26, v27
	v_cvt_pk_bf16_f32 v9, v12, v13
	v_cvt_pk_bf16_f32 v11, v14, v15
	v_lshl_add_u64 v[12:13], v[162:163], 0, s[92:93]
	global_store_dwordx4 v[12:13], v[8:11], off
	s_branch .LBB0_1814
